# out-proj GEMM K loop software-pipelined (fragments of step k+1 prefetched during step k; LDS-DMA through scalar bases); layer-0 norm as a 2-iteration loop
# speedup vs baseline: 1.0168x; 1.0107x over previous
; DI unsigned pk2(float lo, float hi) { unsigned r; asm volatile("v_cvt_pk_bf16_f32 %0, %1, %2" : "=v"(r) : "v"(lo), "v"(hi)); return r; }
; DI float shx(float v, int m, int lane) { return __int_as_float(__builtin_amdgcn_ds_bpermute((lane ^ m) << 2, __float_as_int(v))); }
; DI void norm_rows(const Params& p, int layer, int row0, int nrows, int wstart, int wstride, int tid) {
;     ...
;   for (int rowa = row0 + wstart + wid; rowa < row0 + nrows; rowa += 2 * wstride) {
;     const int rowb = (rowa + wstride < row0 + nrows) ? rowa + wstride : rowa;
;     float4 va[4], vb[4]; float sa = 0.f, sb = 0.f;
; #pragma unroll
;     for (int i = 0; i < 4; ++i) { va[i] = *(const float4*)(xin + (size_t)rowa * DM + i * 256 + lane * 4); vb[i] = *(const float4*)(xin + (size_t)rowb * DM + i * 256 + lane * 4); }
; #pragma unroll
;     for (int i = 0; i < 4; ++i) { sa += va[i].x * va[i].x + va[i].y * va[i].y + va[i].z * va[i].z + va[i].w * va[i].w; sb += vb[i].x * vb[i].x + vb[i].y * vb[i].y + vb[i].z * vb[i].z + vb[i].w * vb[i].w; }
; #pragma unroll
;     for (int o = 32; o >= 1; o >>= 1) { sa += shx(sa, o, lane); sb += shx(sb, o, lane); }
; #pragma unroll
;     for (int rr = 0; rr < 2; ++rr) {
;       const int row = rr ? rowb : rowa; const float rinv = rsqrtf((rr ? sb : sa) * (1.0f / 1024.0f) + EPS);
;       if (layer < NLAYER) {
;         const int b = row >> 13; const float* md = modb + (size_t)(layer * 4 + b) * 3072; const float* g = p.norm_g + layer * 1024;
; #pragma unroll
;         for (int i = 0; i < 4; ++i) {
;           const float4 x4 = rr ? vb[i] : va[i];
;           const int e = i * 256 + lane * 4;
;           const float4 g4 = *(const float4*)(g + e), sh = *(const float4*)(md + e), sc = *(const float4*)(md + 1024 + e);
;           uint2 w;
;           w.x = pk2(x4.x * rinv * g4.x * (1.f + sc.x) + sh.x, x4.y * rinv * g4.y * (1.f + sc.y) + sh.y);
;           w.y = pk2(x4.z * rinv * g4.z * (1.f + sc.z) + sh.z, x4.w * rinv * g4.w * (1.f + sc.w) + sh.w);
;           *(uint2*)(h + wimg_off(row, e, DM)) = w;
.LBB0_91:
	s_cmp_lg_u32 s2, 0
	s_mov_b64 s[0:1], s[36:37]
	s_cbranch_scc1 .LBB0_148
	s_mov_b32 s28, 0
.Lp0n_loop:
	v_readlane_b32 s0, v253, 47
	v_readlane_b32 s4, v252, 2
	v_readlane_b32 s5, v252, 3
	v_readlane_b32 s6, v252, 8
	v_readlane_b32 s7, v252, 9
	v_readlane_b32 s8, v252, 22
	v_readlane_b32 s9, v252, 23
	v_readlane_b32 s18, v252, 48
	v_readlane_b32 s19, v252, 49
	s_lshl_b32 s0, s0, 3
	s_add_i32 s0, s0, s28
	s_lshl_b32 s1, s0, 12
	s_add_u32 s4, s4, s1
	s_addc_u32 s5, s5, 0
	s_add_u32 s6, s6, 0
	s_addc_u32 s7, s7, 0
	s_lshr_b32 s1, s0, 13
	s_mul_i32 s1, s1, 0x3000
	s_add_u32 s8, s8, s1
	s_addc_u32 s9, s9, 0
	s_add_u32 s10, s8, 0x1000
	s_addc_u32 s11, s9, 0
	s_lshr_b32 s1, s0, 7
	s_lshl_b32 s1, s1, 18
	s_bfe_u32 s12, s0, 0x10006
	s_lshl_b32 s12, s12, 12
	s_add_u32 s1, s1, s12
	s_add_u32 s18, s18, s1
	s_addc_u32 s19, s19, 0
	v_and_b32_e32 v245, 63, v163
	v_lshrrev_b32_e32 v246, 6, v163
	v_lshlrev_b32_e32 v247, 2, v245
	v_xor_b32_e32 v236, 0x80, v247
	v_xor_b32_e32 v237, 0x40, v247
	v_xor_b32_e32 v238, 0x20, v247
	v_xor_b32_e32 v239, 0x10, v247
	v_xor_b32_e32 v240, 0x8, v247
	v_xor_b32_e32 v241, 0x4, v247
	v_lshlrev_b32_e32 v245, 4, v245
	v_lshl_add_u32 v242, v246, 12, v245
	v_and_b32_e32 v248, 63, v163
	v_lshrrev_b32_e32 v249, 3, v248
	v_and_b32_e32 v248, 7, v248
	v_lshlrev_b32_e32 v248, 3, v248
	v_lshlrev_b32_e32 v249, 13, v249
	v_lshl_add_u32 v249, v246, 6, v249
	v_add_u32_e32 v243, v249, v248
	v_xor_b32_e32 v248, 32, v248
	v_add_u32_e32 v244, v249, v248
	v_add_u32_e32 v244, 0x200, v244
	global_load_dwordx4 v[128:131], v245, s[6:7] offset:0
	global_load_dwordx4 v[132:135], v245, s[6:7] offset:1024
	global_load_dwordx4 v[136:139], v245, s[6:7] offset:2048
	global_load_dwordx4 v[140:143], v245, s[6:7] offset:3072
	global_load_dwordx4 v[144:147], v245, s[8:9] offset:0
	global_load_dwordx4 v[148:151], v245, s[8:9] offset:1024
	global_load_dwordx4 v[152:155], v245, s[8:9] offset:2048
	global_load_dwordx4 v[156:159], v245, s[8:9] offset:3072
	global_load_dwordx4 v[204:207], v245, s[10:11] offset:0
	global_load_dwordx4 v[208:211], v245, s[10:11] offset:1024
	global_load_dwordx4 v[212:215], v245, s[10:11] offset:2048
	global_load_dwordx4 v[216:219], v245, s[10:11] offset:3072
	global_load_dwordx4 v[0:3], v242, s[4:5] offset:0
	global_load_dwordx4 v[4:7], v242, s[4:5] offset:1024
	global_load_dwordx4 v[8:11], v242, s[4:5] offset:2048
	global_load_dwordx4 v[12:15], v242, s[4:5] offset:3072
	s_add_u32 s4, s4, 0x8000
	s_addc_u32 s5, s5, 0
	global_load_dwordx4 v[16:19], v242, s[4:5] offset:0
	global_load_dwordx4 v[20:23], v242, s[4:5] offset:1024
	global_load_dwordx4 v[24:27], v242, s[4:5] offset:2048
	global_load_dwordx4 v[28:31], v242, s[4:5] offset:3072
	s_add_u32 s4, s4, 0x8000
	s_addc_u32 s5, s5, 0
	global_load_dwordx4 v[32:35], v242, s[4:5] offset:0
	global_load_dwordx4 v[36:39], v242, s[4:5] offset:1024
	global_load_dwordx4 v[40:43], v242, s[4:5] offset:2048
	global_load_dwordx4 v[44:47], v242, s[4:5] offset:3072
	s_add_u32 s4, s4, 0x8000
	s_addc_u32 s5, s5, 0
	global_load_dwordx4 v[48:51], v242, s[4:5] offset:0
	global_load_dwordx4 v[52:55], v242, s[4:5] offset:1024
	global_load_dwordx4 v[56:59], v242, s[4:5] offset:2048
	global_load_dwordx4 v[60:63], v242, s[4:5] offset:3072
	s_add_u32 s4, s4, 0x8000
	s_addc_u32 s5, s5, 0
	global_load_dwordx4 v[64:67], v242, s[4:5] offset:0
	global_load_dwordx4 v[68:71], v242, s[4:5] offset:1024
	global_load_dwordx4 v[72:75], v242, s[4:5] offset:2048
	global_load_dwordx4 v[76:79], v242, s[4:5] offset:3072
	s_add_u32 s4, s4, 0x8000
	s_addc_u32 s5, s5, 0
	global_load_dwordx4 v[80:83], v242, s[4:5] offset:0
	global_load_dwordx4 v[84:87], v242, s[4:5] offset:1024
	global_load_dwordx4 v[88:91], v242, s[4:5] offset:2048
	global_load_dwordx4 v[92:95], v242, s[4:5] offset:3072
	s_add_u32 s4, s4, 0x8000
	s_addc_u32 s5, s5, 0
	global_load_dwordx4 v[96:99], v242, s[4:5] offset:0
	global_load_dwordx4 v[100:103], v242, s[4:5] offset:1024
	global_load_dwordx4 v[104:107], v242, s[4:5] offset:2048
	global_load_dwordx4 v[108:111], v242, s[4:5] offset:3072
	s_add_u32 s4, s4, 0x8000
	s_addc_u32 s5, s5, 0
	global_load_dwordx4 v[112:115], v242, s[4:5] offset:0
	global_load_dwordx4 v[116:119], v242, s[4:5] offset:1024
	global_load_dwordx4 v[120:123], v242, s[4:5] offset:2048
	global_load_dwordx4 v[124:127], v242, s[4:5] offset:3072
	s_add_u32 s20, s18, 0x10000
	s_addc_u32 s21, s19, 0
	s_add_u32 s22, s18, 0x20000
	s_addc_u32 s23, s19, 0
	s_add_u32 s24, s18, 0x30000
	s_addc_u32 s25, s19, 0
	s_mov_b32 s26, 0x3a800000
	s_waitcnt vmcnt(24)
	v_add_f32_e32 v204, 1.0, v204
	v_add_f32_e32 v205, 1.0, v205
	v_add_f32_e32 v206, 1.0, v206
	v_add_f32_e32 v207, 1.0, v207
	v_add_f32_e32 v208, 1.0, v208
	v_add_f32_e32 v209, 1.0, v209
	v_add_f32_e32 v210, 1.0, v210
	v_add_f32_e32 v211, 1.0, v211
	v_add_f32_e32 v212, 1.0, v212
	v_add_f32_e32 v213, 1.0, v213
	v_add_f32_e32 v214, 1.0, v214
	v_add_f32_e32 v215, 1.0, v215
	v_add_f32_e32 v216, 1.0, v216
	v_add_f32_e32 v217, 1.0, v217
	v_add_f32_e32 v218, 1.0, v218
	v_add_f32_e32 v219, 1.0, v219
	v_mul_f32_e32 v220, v1, v1
	v_mul_f32_e32 v224, v17, v17
	v_fmac_f32_e32 v220, v0, v0
	v_fmac_f32_e32 v224, v16, v16
	v_fmac_f32_e32 v220, v2, v2
	v_fmac_f32_e32 v224, v18, v18
	v_fmac_f32_e32 v220, v3, v3
	v_fmac_f32_e32 v224, v19, v19
	v_mul_f32_e32 v221, v5, v5
	v_mul_f32_e32 v225, v21, v21
	v_fmac_f32_e32 v221, v4, v4
	v_fmac_f32_e32 v225, v20, v20
	v_fmac_f32_e32 v221, v6, v6
	v_fmac_f32_e32 v225, v22, v22
	v_fmac_f32_e32 v221, v7, v7
	v_fmac_f32_e32 v225, v23, v23
	v_mul_f32_e32 v222, v9, v9
	v_mul_f32_e32 v226, v25, v25
	v_fmac_f32_e32 v222, v8, v8
	v_fmac_f32_e32 v226, v24, v24
	v_fmac_f32_e32 v222, v10, v10
	v_fmac_f32_e32 v226, v26, v26
	v_fmac_f32_e32 v222, v11, v11
	v_fmac_f32_e32 v226, v27, v27
	v_mul_f32_e32 v223, v13, v13
	v_mul_f32_e32 v227, v29, v29
	v_fmac_f32_e32 v223, v12, v12
	v_fmac_f32_e32 v227, v28, v28
	v_fmac_f32_e32 v223, v14, v14
	v_fmac_f32_e32 v227, v30, v30
	v_fmac_f32_e32 v223, v15, v15
	v_fmac_f32_e32 v227, v31, v31
	v_add_f32_e32 v228, v220, v221
	v_add_f32_e32 v229, v224, v225
	v_add_f32_e32 v228, v228, v222
	v_add_f32_e32 v229, v229, v226
	v_add_f32_e32 v228, v228, v223
	v_add_f32_e32 v229, v229, v227
	ds_bpermute_b32 v230, v236, v228
	ds_bpermute_b32 v231, v236, v229
	s_waitcnt lgkmcnt(0)
; DI unsigned pk2(float lo, float hi) { unsigned r; asm volatile("v_cvt_pk_bf16_f32 %0, %1, %2" : "=v"(r) : "v"(lo), "v"(hi)); return r; }
; DI float shx(float v, int m, int lane) { return __int_as_float(__builtin_amdgcn_ds_bpermute((lane ^ m) << 2, __float_as_int(v))); }
; DI void norm_rows(const Params& p, int layer, int row0, int nrows, int wstart, int wstride, int tid) {
;     ...
;     for (int o = 32; o >= 1; o >>= 1) { sa += shx(sa, o, lane); sb += shx(sb, o, lane); }
; #pragma unroll
;     for (int rr = 0; rr < 2; ++rr) {
;       const int row = rr ? rowb : rowa; const float rinv = rsqrtf((rr ? sb : sa) * (1.0f / 1024.0f) + EPS);
;       if (layer < NLAYER) {
;         const int b = row >> 13; const float* md = modb + (size_t)(layer * 4 + b) * 3072; const float* g = p.norm_g + layer * 1024;
; #pragma unroll
;         for (int i = 0; i < 4; ++i) {
;           const float4 x4 = rr ? vb[i] : va[i];
;           const int e = i * 256 + lane * 4;
;           const float4 g4 = *(const float4*)(g + e), sh = *(const float4*)(md + e), sc = *(const float4*)(md + 1024 + e);
;           uint2 w;
;           w.x = pk2(x4.x * rinv * g4.x * (1.f + sc.x) + sh.x, x4.y * rinv * g4.y * (1.f + sc.y) + sh.y);
;           w.y = pk2(x4.z * rinv * g4.z * (1.f + sc.z) + sh.z, x4.w * rinv * g4.w * (1.f + sc.w) + sh.w);
;           *(uint2*)(h + wimg_off(row, e, DM)) = w;
	v_add_f32_e32 v228, v228, v230
	v_add_f32_e32 v229, v229, v231
	ds_bpermute_b32 v230, v237, v228
	ds_bpermute_b32 v231, v237, v229
	s_waitcnt lgkmcnt(0)
	v_add_f32_e32 v228, v228, v230
	v_add_f32_e32 v229, v229, v231
	ds_bpermute_b32 v230, v238, v228
	ds_bpermute_b32 v231, v238, v229
	s_waitcnt lgkmcnt(0)
	v_add_f32_e32 v228, v228, v230
	v_add_f32_e32 v229, v229, v231
	ds_bpermute_b32 v230, v239, v228
	ds_bpermute_b32 v231, v239, v229
	s_waitcnt lgkmcnt(0)
	v_add_f32_e32 v228, v228, v230
	v_add_f32_e32 v229, v229, v231
	ds_bpermute_b32 v230, v240, v228
	ds_bpermute_b32 v231, v240, v229
	s_waitcnt lgkmcnt(0)
	v_add_f32_e32 v228, v228, v230
	v_add_f32_e32 v229, v229, v231
	ds_bpermute_b32 v230, v241, v228
	ds_bpermute_b32 v231, v241, v229
	s_waitcnt lgkmcnt(0)
	v_add_f32_e32 v228, v228, v230
	v_add_f32_e32 v229, v229, v231
	v_fma_f32 v228, v228, s26, v162
	v_fma_f32 v229, v229, s26, v162
	v_rsq_f32_e32 v232, v228
	v_rsq_f32_e32 v233, v229
	s_nop 0
	v_mul_f32_e32 v0, v0, v232
	v_mul_f32_e32 v1, v1, v232
	v_mul_f32_e32 v2, v2, v232
	v_mul_f32_e32 v3, v3, v232
	v_mul_f32_e32 v0, v128, v0
	v_mul_f32_e32 v1, v129, v1
	v_mul_f32_e32 v2, v130, v2
	v_mul_f32_e32 v3, v131, v3
	v_fma_f32 v0, v0, v204, v144
	v_fma_f32 v1, v1, v205, v145
	v_fma_f32 v2, v2, v206, v146
	v_fma_f32 v3, v3, v207, v147
	v_cvt_pk_bf16_f32 v234, v0, v1
	v_cvt_pk_bf16_f32 v235, v2, v3
	s_nop 0
	global_store_dwordx2 v243, v[234:235], s[18:19] offset:0
	v_mul_f32_e32 v4, v4, v232
	v_mul_f32_e32 v5, v5, v232
	v_mul_f32_e32 v6, v6, v232
	v_mul_f32_e32 v7, v7, v232
	v_mul_f32_e32 v4, v132, v4
	v_mul_f32_e32 v5, v133, v5
	v_mul_f32_e32 v6, v134, v6
	v_mul_f32_e32 v7, v135, v7
	v_fma_f32 v4, v4, v208, v148
	v_fma_f32 v5, v5, v209, v149
	v_fma_f32 v6, v6, v210, v150
	v_fma_f32 v7, v7, v211, v151
	v_cvt_pk_bf16_f32 v234, v4, v5
	v_cvt_pk_bf16_f32 v235, v6, v7
	s_nop 0
	global_store_dwordx2 v243, v[234:235], s[20:21] offset:0
	v_mul_f32_e32 v8, v8, v232
	v_mul_f32_e32 v9, v9, v232
	v_mul_f32_e32 v10, v10, v232
	v_mul_f32_e32 v11, v11, v232
	v_mul_f32_e32 v8, v136, v8
	v_mul_f32_e32 v9, v137, v9
	v_mul_f32_e32 v10, v138, v10
	v_mul_f32_e32 v11, v139, v11
	v_fma_f32 v8, v8, v212, v152
	v_fma_f32 v9, v9, v213, v153
	v_fma_f32 v10, v10, v214, v154
	v_fma_f32 v11, v11, v215, v155
	v_cvt_pk_bf16_f32 v234, v8, v9
	v_cvt_pk_bf16_f32 v235, v10, v11
	s_nop 0
	global_store_dwordx2 v243, v[234:235], s[22:23] offset:0
	v_mul_f32_e32 v12, v12, v232
	v_mul_f32_e32 v13, v13, v232
	v_mul_f32_e32 v14, v14, v232
	v_mul_f32_e32 v15, v15, v232
	v_mul_f32_e32 v12, v140, v12
	v_mul_f32_e32 v13, v141, v13
	v_mul_f32_e32 v14, v142, v14
	v_mul_f32_e32 v15, v143, v15
	v_fma_f32 v12, v12, v216, v156
	v_fma_f32 v13, v13, v217, v157
	v_fma_f32 v14, v14, v218, v158
	v_fma_f32 v15, v15, v219, v159
	v_cvt_pk_bf16_f32 v234, v12, v13
	v_cvt_pk_bf16_f32 v235, v14, v15
	s_nop 0
	global_store_dwordx2 v243, v[234:235], s[24:25] offset:0
	v_mul_f32_e32 v16, v16, v233
	v_mul_f32_e32 v17, v17, v233
	v_mul_f32_e32 v18, v18, v233
	v_mul_f32_e32 v19, v19, v233
	v_mul_f32_e32 v16, v128, v16
	v_mul_f32_e32 v17, v129, v17
	v_mul_f32_e32 v18, v130, v18
	v_mul_f32_e32 v19, v131, v19
	v_fma_f32 v16, v16, v204, v144
	v_fma_f32 v17, v17, v205, v145
	v_fma_f32 v18, v18, v206, v146
	v_fma_f32 v19, v19, v207, v147
	v_cvt_pk_bf16_f32 v234, v16, v17
	v_cvt_pk_bf16_f32 v235, v18, v19
	s_nop 0
	global_store_dwordx2 v244, v[234:235], s[18:19] offset:0
	v_mul_f32_e32 v20, v20, v233
	v_mul_f32_e32 v21, v21, v233
	v_mul_f32_e32 v22, v22, v233
	v_mul_f32_e32 v23, v23, v233
	v_mul_f32_e32 v20, v132, v20
	v_mul_f32_e32 v21, v133, v21
	v_mul_f32_e32 v22, v134, v22
	v_mul_f32_e32 v23, v135, v23
	v_fma_f32 v20, v20, v208, v148
	v_fma_f32 v21, v21, v209, v149
	v_fma_f32 v22, v22, v210, v150
	v_fma_f32 v23, v23, v211, v151
	v_cvt_pk_bf16_f32 v234, v20, v21
	v_cvt_pk_bf16_f32 v235, v22, v23
	s_nop 0
	global_store_dwordx2 v244, v[234:235], s[20:21] offset:0
	v_mul_f32_e32 v24, v24, v233
	v_mul_f32_e32 v25, v25, v233
	v_mul_f32_e32 v26, v26, v233
	v_mul_f32_e32 v27, v27, v233
	v_mul_f32_e32 v24, v136, v24
	v_mul_f32_e32 v25, v137, v25
	v_mul_f32_e32 v26, v138, v26
	v_mul_f32_e32 v27, v139, v27
	v_fma_f32 v24, v24, v212, v152
	v_fma_f32 v25, v25, v213, v153
	v_fma_f32 v26, v26, v214, v154
	v_fma_f32 v27, v27, v215, v155
	v_cvt_pk_bf16_f32 v234, v24, v25
	v_cvt_pk_bf16_f32 v235, v26, v27
	s_nop 0
	global_store_dwordx2 v244, v[234:235], s[22:23] offset:0
	v_mul_f32_e32 v28, v28, v233
	v_mul_f32_e32 v29, v29, v233
	v_mul_f32_e32 v30, v30, v233
	v_mul_f32_e32 v31, v31, v233
	v_mul_f32_e32 v28, v140, v28
	v_mul_f32_e32 v29, v141, v29
	v_mul_f32_e32 v30, v142, v30
	v_mul_f32_e32 v31, v143, v31
	v_fma_f32 v28, v28, v216, v156
	v_fma_f32 v29, v29, v217, v157
	v_fma_f32 v30, v30, v218, v158
	v_fma_f32 v31, v31, v219, v159
	v_cvt_pk_bf16_f32 v234, v28, v29
	v_cvt_pk_bf16_f32 v235, v30, v31
	s_nop 0
	global_store_dwordx2 v244, v[234:235], s[24:25] offset:0
	s_waitcnt vmcnt(24)
	v_mul_f32_e32 v220, v33, v33
	v_mul_f32_e32 v224, v49, v49
	v_fmac_f32_e32 v220, v32, v32
	v_fmac_f32_e32 v224, v48, v48
	v_fmac_f32_e32 v220, v34, v34
	v_fmac_f32_e32 v224, v50, v50
	v_fmac_f32_e32 v220, v35, v35
	v_fmac_f32_e32 v224, v51, v51
	v_mul_f32_e32 v221, v37, v37
	v_mul_f32_e32 v225, v53, v53
	v_fmac_f32_e32 v221, v36, v36
	v_fmac_f32_e32 v225, v52, v52
	v_fmac_f32_e32 v221, v38, v38
	v_fmac_f32_e32 v225, v54, v54
	v_fmac_f32_e32 v221, v39, v39
	v_fmac_f32_e32 v225, v55, v55
	v_mul_f32_e32 v222, v41, v41
	v_mul_f32_e32 v226, v57, v57
	v_fmac_f32_e32 v222, v40, v40
	v_fmac_f32_e32 v226, v56, v56
	v_fmac_f32_e32 v222, v42, v42
	v_fmac_f32_e32 v226, v58, v58
	v_fmac_f32_e32 v222, v43, v43
	v_fmac_f32_e32 v226, v59, v59
	v_mul_f32_e32 v223, v45, v45
	v_mul_f32_e32 v227, v61, v61
	v_fmac_f32_e32 v223, v44, v44
	v_fmac_f32_e32 v227, v60, v60
	v_fmac_f32_e32 v223, v46, v46
	v_fmac_f32_e32 v227, v62, v62
	v_fmac_f32_e32 v223, v47, v47
	v_fmac_f32_e32 v227, v63, v63
	v_add_f32_e32 v228, v220, v221
	v_add_f32_e32 v229, v224, v225
	v_add_f32_e32 v228, v228, v222
	v_add_f32_e32 v229, v229, v226
	v_add_f32_e32 v228, v228, v223
	v_add_f32_e32 v229, v229, v227
	ds_bpermute_b32 v230, v236, v228
	ds_bpermute_b32 v231, v236, v229
	s_waitcnt lgkmcnt(0)
; DI unsigned pk2(float lo, float hi) { unsigned r; asm volatile("v_cvt_pk_bf16_f32 %0, %1, %2" : "=v"(r) : "v"(lo), "v"(hi)); return r; }
; DI float shx(float v, int m, int lane) { return __int_as_float(__builtin_amdgcn_ds_bpermute((lane ^ m) << 2, __float_as_int(v))); }
; DI void norm_rows(const Params& p, int layer, int row0, int nrows, int wstart, int wstride, int tid) {
;     ...
;     for (int o = 32; o >= 1; o >>= 1) { sa += shx(sa, o, lane); sb += shx(sb, o, lane); }
; #pragma unroll
;     for (int rr = 0; rr < 2; ++rr) {
;       const int row = rr ? rowb : rowa; const float rinv = rsqrtf((rr ? sb : sa) * (1.0f / 1024.0f) + EPS);
;       if (layer < NLAYER) {
;         const int b = row >> 13; const float* md = modb + (size_t)(layer * 4 + b) * 3072; const float* g = p.norm_g + layer * 1024;
; #pragma unroll
;         for (int i = 0; i < 4; ++i) {
;           const float4 x4 = rr ? vb[i] : va[i];
;           const int e = i * 256 + lane * 4;
;           const float4 g4 = *(const float4*)(g + e), sh = *(const float4*)(md + e), sc = *(const float4*)(md + 1024 + e);
;           uint2 w;
;           w.x = pk2(x4.x * rinv * g4.x * (1.f + sc.x) + sh.x, x4.y * rinv * g4.y * (1.f + sc.y) + sh.y);
;           w.y = pk2(x4.z * rinv * g4.z * (1.f + sc.z) + sh.z, x4.w * rinv * g4.w * (1.f + sc.w) + sh.w);
;           *(uint2*)(h + wimg_off(row, e, DM)) = w;
	v_add_f32_e32 v228, v228, v230
	v_add_f32_e32 v229, v229, v231
	ds_bpermute_b32 v230, v237, v228
	ds_bpermute_b32 v231, v237, v229
	s_waitcnt lgkmcnt(0)
	v_add_f32_e32 v228, v228, v230
	v_add_f32_e32 v229, v229, v231
	ds_bpermute_b32 v230, v238, v228
	ds_bpermute_b32 v231, v238, v229
	s_waitcnt lgkmcnt(0)
	v_add_f32_e32 v228, v228, v230
	v_add_f32_e32 v229, v229, v231
	ds_bpermute_b32 v230, v239, v228
	ds_bpermute_b32 v231, v239, v229
	s_waitcnt lgkmcnt(0)
	v_add_f32_e32 v228, v228, v230
	v_add_f32_e32 v229, v229, v231
	ds_bpermute_b32 v230, v240, v228
	ds_bpermute_b32 v231, v240, v229
	s_waitcnt lgkmcnt(0)
	v_add_f32_e32 v228, v228, v230
	v_add_f32_e32 v229, v229, v231
	ds_bpermute_b32 v230, v241, v228
	ds_bpermute_b32 v231, v241, v229
	s_waitcnt lgkmcnt(0)
	v_add_f32_e32 v228, v228, v230
	v_add_f32_e32 v229, v229, v231
	v_fma_f32 v228, v228, s26, v162
	v_fma_f32 v229, v229, s26, v162
	v_rsq_f32_e32 v232, v228
	v_rsq_f32_e32 v233, v229
	s_nop 0
	v_mul_f32_e32 v32, v32, v232
	v_mul_f32_e32 v33, v33, v232
	v_mul_f32_e32 v34, v34, v232
	v_mul_f32_e32 v35, v35, v232
	v_mul_f32_e32 v32, v128, v32
	v_mul_f32_e32 v33, v129, v33
	v_mul_f32_e32 v34, v130, v34
	v_mul_f32_e32 v35, v131, v35
	v_fma_f32 v32, v32, v204, v144
	v_fma_f32 v33, v33, v205, v145
	v_fma_f32 v34, v34, v206, v146
	v_fma_f32 v35, v35, v207, v147
	v_cvt_pk_bf16_f32 v234, v32, v33
	v_cvt_pk_bf16_f32 v235, v34, v35
	s_nop 0
	global_store_dwordx2 v243, v[234:235], s[18:19] offset:1024
	v_mul_f32_e32 v36, v36, v232
	v_mul_f32_e32 v37, v37, v232
	v_mul_f32_e32 v38, v38, v232
	v_mul_f32_e32 v39, v39, v232
	v_mul_f32_e32 v36, v132, v36
	v_mul_f32_e32 v37, v133, v37
	v_mul_f32_e32 v38, v134, v38
	v_mul_f32_e32 v39, v135, v39
	v_fma_f32 v36, v36, v208, v148
	v_fma_f32 v37, v37, v209, v149
	v_fma_f32 v38, v38, v210, v150
	v_fma_f32 v39, v39, v211, v151
	v_cvt_pk_bf16_f32 v234, v36, v37
	v_cvt_pk_bf16_f32 v235, v38, v39
	s_nop 0
	global_store_dwordx2 v243, v[234:235], s[20:21] offset:1024
	v_mul_f32_e32 v40, v40, v232
	v_mul_f32_e32 v41, v41, v232
	v_mul_f32_e32 v42, v42, v232
	v_mul_f32_e32 v43, v43, v232
	v_mul_f32_e32 v40, v136, v40
	v_mul_f32_e32 v41, v137, v41
	v_mul_f32_e32 v42, v138, v42
	v_mul_f32_e32 v43, v139, v43
	v_fma_f32 v40, v40, v212, v152
	v_fma_f32 v41, v41, v213, v153
	v_fma_f32 v42, v42, v214, v154
	v_fma_f32 v43, v43, v215, v155
	v_cvt_pk_bf16_f32 v234, v40, v41
	v_cvt_pk_bf16_f32 v235, v42, v43
	s_nop 0
	global_store_dwordx2 v243, v[234:235], s[22:23] offset:1024
	v_mul_f32_e32 v44, v44, v232
	v_mul_f32_e32 v45, v45, v232
	v_mul_f32_e32 v46, v46, v232
	v_mul_f32_e32 v47, v47, v232
	v_mul_f32_e32 v44, v140, v44
	v_mul_f32_e32 v45, v141, v45
	v_mul_f32_e32 v46, v142, v46
	v_mul_f32_e32 v47, v143, v47
	v_fma_f32 v44, v44, v216, v156
	v_fma_f32 v45, v45, v217, v157
	v_fma_f32 v46, v46, v218, v158
	v_fma_f32 v47, v47, v219, v159
	v_cvt_pk_bf16_f32 v234, v44, v45
	v_cvt_pk_bf16_f32 v235, v46, v47
	s_nop 0
	global_store_dwordx2 v243, v[234:235], s[24:25] offset:1024
	v_mul_f32_e32 v48, v48, v233
	v_mul_f32_e32 v49, v49, v233
	v_mul_f32_e32 v50, v50, v233
	v_mul_f32_e32 v51, v51, v233
	v_mul_f32_e32 v48, v128, v48
	v_mul_f32_e32 v49, v129, v49
	v_mul_f32_e32 v50, v130, v50
	v_mul_f32_e32 v51, v131, v51
	v_fma_f32 v48, v48, v204, v144
	v_fma_f32 v49, v49, v205, v145
	v_fma_f32 v50, v50, v206, v146
	v_fma_f32 v51, v51, v207, v147
	v_cvt_pk_bf16_f32 v234, v48, v49
	v_cvt_pk_bf16_f32 v235, v50, v51
	s_nop 0
	global_store_dwordx2 v244, v[234:235], s[18:19] offset:1024
	v_mul_f32_e32 v52, v52, v233
	v_mul_f32_e32 v53, v53, v233
	v_mul_f32_e32 v54, v54, v233
	v_mul_f32_e32 v55, v55, v233
	v_mul_f32_e32 v52, v132, v52
	v_mul_f32_e32 v53, v133, v53
	v_mul_f32_e32 v54, v134, v54
	v_mul_f32_e32 v55, v135, v55
	v_fma_f32 v52, v52, v208, v148
	v_fma_f32 v53, v53, v209, v149
	v_fma_f32 v54, v54, v210, v150
	v_fma_f32 v55, v55, v211, v151
	v_cvt_pk_bf16_f32 v234, v52, v53
	v_cvt_pk_bf16_f32 v235, v54, v55
	s_nop 0
	global_store_dwordx2 v244, v[234:235], s[20:21] offset:1024
	v_mul_f32_e32 v56, v56, v233
	v_mul_f32_e32 v57, v57, v233
	v_mul_f32_e32 v58, v58, v233
	v_mul_f32_e32 v59, v59, v233
	v_mul_f32_e32 v56, v136, v56
	v_mul_f32_e32 v57, v137, v57
	v_mul_f32_e32 v58, v138, v58
	v_mul_f32_e32 v59, v139, v59
	v_fma_f32 v56, v56, v212, v152
	v_fma_f32 v57, v57, v213, v153
	v_fma_f32 v58, v58, v214, v154
	v_fma_f32 v59, v59, v215, v155
	v_cvt_pk_bf16_f32 v234, v56, v57
	v_cvt_pk_bf16_f32 v235, v58, v59
	s_nop 0
	global_store_dwordx2 v244, v[234:235], s[22:23] offset:1024
	v_mul_f32_e32 v60, v60, v233
	v_mul_f32_e32 v61, v61, v233
	v_mul_f32_e32 v62, v62, v233
	v_mul_f32_e32 v63, v63, v233
	v_mul_f32_e32 v60, v140, v60
	v_mul_f32_e32 v61, v141, v61
	v_mul_f32_e32 v62, v142, v62
	v_mul_f32_e32 v63, v143, v63
	v_fma_f32 v60, v60, v216, v156
	v_fma_f32 v61, v61, v217, v157
	v_fma_f32 v62, v62, v218, v158
	v_fma_f32 v63, v63, v219, v159
	v_cvt_pk_bf16_f32 v234, v60, v61
	v_cvt_pk_bf16_f32 v235, v62, v63
	s_nop 0
	global_store_dwordx2 v244, v[234:235], s[24:25] offset:1024
	s_waitcnt vmcnt(24)
; DI unsigned pk2(float lo, float hi) { unsigned r; asm volatile("v_cvt_pk_bf16_f32 %0, %1, %2" : "=v"(r) : "v"(lo), "v"(hi)); return r; }
; DI float shx(float v, int m, int lane) { return __int_as_float(__builtin_amdgcn_ds_bpermute((lane ^ m) << 2, __float_as_int(v))); }
; DI void norm_rows(const Params& p, int layer, int row0, int nrows, int wstart, int wstride, int tid) {
;     ...
;     for (int o = 32; o >= 1; o >>= 1) { sa += shx(sa, o, lane); sb += shx(sb, o, lane); }
; #pragma unroll
;     for (int rr = 0; rr < 2; ++rr) {
;       const int row = rr ? rowb : rowa; const float rinv = rsqrtf((rr ? sb : sa) * (1.0f / 1024.0f) + EPS);
;       if (layer < NLAYER) {
;         const int b = row >> 13; const float* md = modb + (size_t)(layer * 4 + b) * 3072; const float* g = p.norm_g + layer * 1024;
; #pragma unroll
;         for (int i = 0; i < 4; ++i) {
;           const float4 x4 = rr ? vb[i] : va[i];
;           const int e = i * 256 + lane * 4;
;           const float4 g4 = *(const float4*)(g + e), sh = *(const float4*)(md + e), sc = *(const float4*)(md + 1024 + e);
;           uint2 w;
;           w.x = pk2(x4.x * rinv * g4.x * (1.f + sc.x) + sh.x, x4.y * rinv * g4.y * (1.f + sc.y) + sh.y);
;           w.y = pk2(x4.z * rinv * g4.z * (1.f + sc.z) + sh.z, x4.w * rinv * g4.w * (1.f + sc.w) + sh.w);
;           *(uint2*)(h + wimg_off(row, e, DM)) = w;
	v_mul_f32_e32 v220, v65, v65
	v_mul_f32_e32 v224, v81, v81
	v_fmac_f32_e32 v220, v64, v64
	v_fmac_f32_e32 v224, v80, v80
	v_fmac_f32_e32 v220, v66, v66
	v_fmac_f32_e32 v224, v82, v82
	v_fmac_f32_e32 v220, v67, v67
	v_fmac_f32_e32 v224, v83, v83
	v_mul_f32_e32 v221, v69, v69
	v_mul_f32_e32 v225, v85, v85
	v_fmac_f32_e32 v221, v68, v68
	v_fmac_f32_e32 v225, v84, v84
	v_fmac_f32_e32 v221, v70, v70
	v_fmac_f32_e32 v225, v86, v86
	v_fmac_f32_e32 v221, v71, v71
	v_fmac_f32_e32 v225, v87, v87
	v_mul_f32_e32 v222, v73, v73
	v_mul_f32_e32 v226, v89, v89
	v_fmac_f32_e32 v222, v72, v72
	v_fmac_f32_e32 v226, v88, v88
	v_fmac_f32_e32 v222, v74, v74
	v_fmac_f32_e32 v226, v90, v90
	v_fmac_f32_e32 v222, v75, v75
	v_fmac_f32_e32 v226, v91, v91
	v_mul_f32_e32 v223, v77, v77
	v_mul_f32_e32 v227, v93, v93
	v_fmac_f32_e32 v223, v76, v76
	v_fmac_f32_e32 v227, v92, v92
	v_fmac_f32_e32 v223, v78, v78
	v_fmac_f32_e32 v227, v94, v94
	v_fmac_f32_e32 v223, v79, v79
	v_fmac_f32_e32 v227, v95, v95
	v_add_f32_e32 v228, v220, v221
	v_add_f32_e32 v229, v224, v225
	v_add_f32_e32 v228, v228, v222
	v_add_f32_e32 v229, v229, v226
	v_add_f32_e32 v228, v228, v223
	v_add_f32_e32 v229, v229, v227
	ds_bpermute_b32 v230, v236, v228
	ds_bpermute_b32 v231, v236, v229
	s_waitcnt lgkmcnt(0)
	v_add_f32_e32 v228, v228, v230
	v_add_f32_e32 v229, v229, v231
	ds_bpermute_b32 v230, v237, v228
	ds_bpermute_b32 v231, v237, v229
	s_waitcnt lgkmcnt(0)
	v_add_f32_e32 v228, v228, v230
	v_add_f32_e32 v229, v229, v231
	ds_bpermute_b32 v230, v238, v228
	ds_bpermute_b32 v231, v238, v229
	s_waitcnt lgkmcnt(0)
	v_add_f32_e32 v228, v228, v230
	v_add_f32_e32 v229, v229, v231
	ds_bpermute_b32 v230, v239, v228
	ds_bpermute_b32 v231, v239, v229
	s_waitcnt lgkmcnt(0)
	v_add_f32_e32 v228, v228, v230
	v_add_f32_e32 v229, v229, v231
	ds_bpermute_b32 v230, v240, v228
	ds_bpermute_b32 v231, v240, v229
	s_waitcnt lgkmcnt(0)
	v_add_f32_e32 v228, v228, v230
	v_add_f32_e32 v229, v229, v231
	ds_bpermute_b32 v230, v241, v228
	ds_bpermute_b32 v231, v241, v229
	s_waitcnt lgkmcnt(0)
	v_add_f32_e32 v228, v228, v230
	v_add_f32_e32 v229, v229, v231
	v_fma_f32 v228, v228, s26, v162
	v_fma_f32 v229, v229, s26, v162
	v_rsq_f32_e32 v232, v228
	v_rsq_f32_e32 v233, v229
	s_nop 0
	v_mul_f32_e32 v64, v64, v232
	v_mul_f32_e32 v65, v65, v232
	v_mul_f32_e32 v66, v66, v232
	v_mul_f32_e32 v67, v67, v232
	v_mul_f32_e32 v64, v128, v64
	v_mul_f32_e32 v65, v129, v65
	v_mul_f32_e32 v66, v130, v66
	v_mul_f32_e32 v67, v131, v67
	v_fma_f32 v64, v64, v204, v144
	v_fma_f32 v65, v65, v205, v145
	v_fma_f32 v66, v66, v206, v146
	v_fma_f32 v67, v67, v207, v147
	v_cvt_pk_bf16_f32 v234, v64, v65
	v_cvt_pk_bf16_f32 v235, v66, v67
	s_nop 0
	global_store_dwordx2 v243, v[234:235], s[18:19] offset:2048
	v_mul_f32_e32 v68, v68, v232
	v_mul_f32_e32 v69, v69, v232
	v_mul_f32_e32 v70, v70, v232
	v_mul_f32_e32 v71, v71, v232
	v_mul_f32_e32 v68, v132, v68
	v_mul_f32_e32 v69, v133, v69
	v_mul_f32_e32 v70, v134, v70
	v_mul_f32_e32 v71, v135, v71
	v_fma_f32 v68, v68, v208, v148
	v_fma_f32 v69, v69, v209, v149
	v_fma_f32 v70, v70, v210, v150
	v_fma_f32 v71, v71, v211, v151
	v_cvt_pk_bf16_f32 v234, v68, v69
	v_cvt_pk_bf16_f32 v235, v70, v71
	s_nop 0
	global_store_dwordx2 v243, v[234:235], s[20:21] offset:2048
	v_mul_f32_e32 v72, v72, v232
	v_mul_f32_e32 v73, v73, v232
	v_mul_f32_e32 v74, v74, v232
	v_mul_f32_e32 v75, v75, v232
	v_mul_f32_e32 v72, v136, v72
	v_mul_f32_e32 v73, v137, v73
	v_mul_f32_e32 v74, v138, v74
	v_mul_f32_e32 v75, v139, v75
	v_fma_f32 v72, v72, v212, v152
	v_fma_f32 v73, v73, v213, v153
	v_fma_f32 v74, v74, v214, v154
	v_fma_f32 v75, v75, v215, v155
	v_cvt_pk_bf16_f32 v234, v72, v73
	v_cvt_pk_bf16_f32 v235, v74, v75
	s_nop 0
	global_store_dwordx2 v243, v[234:235], s[22:23] offset:2048
	v_mul_f32_e32 v76, v76, v232
	v_mul_f32_e32 v77, v77, v232
	v_mul_f32_e32 v78, v78, v232
	v_mul_f32_e32 v79, v79, v232
	v_mul_f32_e32 v76, v140, v76
	v_mul_f32_e32 v77, v141, v77
	v_mul_f32_e32 v78, v142, v78
	v_mul_f32_e32 v79, v143, v79
	v_fma_f32 v76, v76, v216, v156
	v_fma_f32 v77, v77, v217, v157
	v_fma_f32 v78, v78, v218, v158
	v_fma_f32 v79, v79, v219, v159
	v_cvt_pk_bf16_f32 v234, v76, v77
	v_cvt_pk_bf16_f32 v235, v78, v79
	s_nop 0
	global_store_dwordx2 v243, v[234:235], s[24:25] offset:2048
	v_mul_f32_e32 v80, v80, v233
	v_mul_f32_e32 v81, v81, v233
	v_mul_f32_e32 v82, v82, v233
	v_mul_f32_e32 v83, v83, v233
	v_mul_f32_e32 v80, v128, v80
	v_mul_f32_e32 v81, v129, v81
	v_mul_f32_e32 v82, v130, v82
	v_mul_f32_e32 v83, v131, v83
	v_fma_f32 v80, v80, v204, v144
	v_fma_f32 v81, v81, v205, v145
	v_fma_f32 v82, v82, v206, v146
	v_fma_f32 v83, v83, v207, v147
	v_cvt_pk_bf16_f32 v234, v80, v81
	v_cvt_pk_bf16_f32 v235, v82, v83
	s_nop 0
	global_store_dwordx2 v244, v[234:235], s[18:19] offset:2048
	v_mul_f32_e32 v84, v84, v233
	v_mul_f32_e32 v85, v85, v233
	v_mul_f32_e32 v86, v86, v233
	v_mul_f32_e32 v87, v87, v233
	v_mul_f32_e32 v84, v132, v84
	v_mul_f32_e32 v85, v133, v85
	v_mul_f32_e32 v86, v134, v86
	v_mul_f32_e32 v87, v135, v87
	v_fma_f32 v84, v84, v208, v148
	v_fma_f32 v85, v85, v209, v149
	v_fma_f32 v86, v86, v210, v150
	v_fma_f32 v87, v87, v211, v151
	v_cvt_pk_bf16_f32 v234, v84, v85
	v_cvt_pk_bf16_f32 v235, v86, v87
	s_nop 0
	global_store_dwordx2 v244, v[234:235], s[20:21] offset:2048
	v_mul_f32_e32 v88, v88, v233
	v_mul_f32_e32 v89, v89, v233
	v_mul_f32_e32 v90, v90, v233
	v_mul_f32_e32 v91, v91, v233
	v_mul_f32_e32 v88, v136, v88
	v_mul_f32_e32 v89, v137, v89
	v_mul_f32_e32 v90, v138, v90
	v_mul_f32_e32 v91, v139, v91
	v_fma_f32 v88, v88, v212, v152
	v_fma_f32 v89, v89, v213, v153
	v_fma_f32 v90, v90, v214, v154
	v_fma_f32 v91, v91, v215, v155
	v_cvt_pk_bf16_f32 v234, v88, v89
	v_cvt_pk_bf16_f32 v235, v90, v91
	s_nop 0
	global_store_dwordx2 v244, v[234:235], s[22:23] offset:2048
	v_mul_f32_e32 v92, v92, v233
	v_mul_f32_e32 v93, v93, v233
	v_mul_f32_e32 v94, v94, v233
	v_mul_f32_e32 v95, v95, v233
	v_mul_f32_e32 v92, v140, v92
	v_mul_f32_e32 v93, v141, v93
	v_mul_f32_e32 v94, v142, v94
	v_mul_f32_e32 v95, v143, v95
	v_fma_f32 v92, v92, v216, v156
	v_fma_f32 v93, v93, v217, v157
	v_fma_f32 v94, v94, v218, v158
	v_fma_f32 v95, v95, v219, v159
	v_cvt_pk_bf16_f32 v234, v92, v93
	v_cvt_pk_bf16_f32 v235, v94, v95
	s_nop 0
	global_store_dwordx2 v244, v[234:235], s[24:25] offset:2048
	s_waitcnt vmcnt(24)
; DI unsigned pk2(float lo, float hi) { unsigned r; asm volatile("v_cvt_pk_bf16_f32 %0, %1, %2" : "=v"(r) : "v"(lo), "v"(hi)); return r; }
; DI float shx(float v, int m, int lane) { return __int_as_float(__builtin_amdgcn_ds_bpermute((lane ^ m) << 2, __float_as_int(v))); }
; DI void norm_rows(const Params& p, int layer, int row0, int nrows, int wstart, int wstride, int tid) {
;     ...
;   for (int rowa = row0 + wstart + wid; rowa < row0 + nrows; rowa += 2 * wstride) {
;     const int rowb = (rowa + wstride < row0 + nrows) ? rowa + wstride : rowa;
;     float4 va[4], vb[4]; float sa = 0.f, sb = 0.f;
; #pragma unroll
;     for (int i = 0; i < 4; ++i) { va[i] = *(const float4*)(xin + (size_t)rowa * DM + i * 256 + lane * 4); vb[i] = *(const float4*)(xin + (size_t)rowb * DM + i * 256 + lane * 4); }
; #pragma unroll
;     for (int i = 0; i < 4; ++i) { sa += va[i].x * va[i].x + va[i].y * va[i].y + va[i].z * va[i].z + va[i].w * va[i].w; sb += vb[i].x * vb[i].x + vb[i].y * vb[i].y + vb[i].z * vb[i].z + vb[i].w * vb[i].w; }
; #pragma unroll
;     for (int o = 32; o >= 1; o >>= 1) { sa += shx(sa, o, lane); sb += shx(sb, o, lane); }
; #pragma unroll
;     for (int rr = 0; rr < 2; ++rr) {
;       const int row = rr ? rowb : rowa; const float rinv = rsqrtf((rr ? sb : sa) * (1.0f / 1024.0f) + EPS);
;       if (layer < NLAYER) {
;         const int b = row >> 13; const float* md = modb + (size_t)(layer * 4 + b) * 3072; const float* g = p.norm_g + layer * 1024;
; #pragma unroll
;         for (int i = 0; i < 4; ++i) {
;           const float4 x4 = rr ? vb[i] : va[i];
;           const int e = i * 256 + lane * 4;
;           const float4 g4 = *(const float4*)(g + e), sh = *(const float4*)(md + e), sc = *(const float4*)(md + 1024 + e);
;           uint2 w;
;           w.x = pk2(x4.x * rinv * g4.x * (1.f + sc.x) + sh.x, x4.y * rinv * g4.y * (1.f + sc.y) + sh.y);
;           w.y = pk2(x4.z * rinv * g4.z * (1.f + sc.z) + sh.z, x4.w * rinv * g4.w * (1.f + sc.w) + sh.w);
;           *(uint2*)(h + wimg_off(row, e, DM)) = w;
	v_mul_f32_e32 v220, v97, v97
	v_mul_f32_e32 v224, v113, v113
	v_fmac_f32_e32 v220, v96, v96
	v_fmac_f32_e32 v224, v112, v112
	v_fmac_f32_e32 v220, v98, v98
	v_fmac_f32_e32 v224, v114, v114
	v_fmac_f32_e32 v220, v99, v99
	v_fmac_f32_e32 v224, v115, v115
	v_mul_f32_e32 v221, v101, v101
	v_mul_f32_e32 v225, v117, v117
	v_fmac_f32_e32 v221, v100, v100
	v_fmac_f32_e32 v225, v116, v116
	v_fmac_f32_e32 v221, v102, v102
	v_fmac_f32_e32 v225, v118, v118
	v_fmac_f32_e32 v221, v103, v103
	v_fmac_f32_e32 v225, v119, v119
	v_mul_f32_e32 v222, v105, v105
	v_mul_f32_e32 v226, v121, v121
	v_fmac_f32_e32 v222, v104, v104
	v_fmac_f32_e32 v226, v120, v120
	v_fmac_f32_e32 v222, v106, v106
	v_fmac_f32_e32 v226, v122, v122
	v_fmac_f32_e32 v222, v107, v107
	v_fmac_f32_e32 v226, v123, v123
	v_mul_f32_e32 v223, v109, v109
	v_mul_f32_e32 v227, v125, v125
	v_fmac_f32_e32 v223, v108, v108
	v_fmac_f32_e32 v227, v124, v124
	v_fmac_f32_e32 v223, v110, v110
	v_fmac_f32_e32 v227, v126, v126
	v_fmac_f32_e32 v223, v111, v111
	v_fmac_f32_e32 v227, v127, v127
	v_add_f32_e32 v228, v220, v221
	v_add_f32_e32 v229, v224, v225
	v_add_f32_e32 v228, v228, v222
	v_add_f32_e32 v229, v229, v226
	v_add_f32_e32 v228, v228, v223
	v_add_f32_e32 v229, v229, v227
	ds_bpermute_b32 v230, v236, v228
	ds_bpermute_b32 v231, v236, v229
	s_waitcnt lgkmcnt(0)
	v_add_f32_e32 v228, v228, v230
	v_add_f32_e32 v229, v229, v231
	ds_bpermute_b32 v230, v237, v228
	ds_bpermute_b32 v231, v237, v229
	s_waitcnt lgkmcnt(0)
	v_add_f32_e32 v228, v228, v230
	v_add_f32_e32 v229, v229, v231
	ds_bpermute_b32 v230, v238, v228
	ds_bpermute_b32 v231, v238, v229
	s_waitcnt lgkmcnt(0)
	v_add_f32_e32 v228, v228, v230
	v_add_f32_e32 v229, v229, v231
	ds_bpermute_b32 v230, v239, v228
	ds_bpermute_b32 v231, v239, v229
	s_waitcnt lgkmcnt(0)
	v_add_f32_e32 v228, v228, v230
	v_add_f32_e32 v229, v229, v231
	ds_bpermute_b32 v230, v240, v228
	ds_bpermute_b32 v231, v240, v229
	s_waitcnt lgkmcnt(0)
	v_add_f32_e32 v228, v228, v230
	v_add_f32_e32 v229, v229, v231
	ds_bpermute_b32 v230, v241, v228
	ds_bpermute_b32 v231, v241, v229
	s_waitcnt lgkmcnt(0)
	v_add_f32_e32 v228, v228, v230
	v_add_f32_e32 v229, v229, v231
	v_fma_f32 v228, v228, s26, v162
	v_fma_f32 v229, v229, s26, v162
	v_rsq_f32_e32 v232, v228
	v_rsq_f32_e32 v233, v229
	s_nop 0
	v_mul_f32_e32 v96, v96, v232
	v_mul_f32_e32 v97, v97, v232
	v_mul_f32_e32 v98, v98, v232
	v_mul_f32_e32 v99, v99, v232
	v_mul_f32_e32 v96, v128, v96
	v_mul_f32_e32 v97, v129, v97
	v_mul_f32_e32 v98, v130, v98
	v_mul_f32_e32 v99, v131, v99
	v_fma_f32 v96, v96, v204, v144
	v_fma_f32 v97, v97, v205, v145
	v_fma_f32 v98, v98, v206, v146
	v_fma_f32 v99, v99, v207, v147
	v_cvt_pk_bf16_f32 v234, v96, v97
	v_cvt_pk_bf16_f32 v235, v98, v99
	s_nop 0
	global_store_dwordx2 v243, v[234:235], s[18:19] offset:3072
	v_mul_f32_e32 v100, v100, v232
	v_mul_f32_e32 v101, v101, v232
	v_mul_f32_e32 v102, v102, v232
	v_mul_f32_e32 v103, v103, v232
	v_mul_f32_e32 v100, v132, v100
	v_mul_f32_e32 v101, v133, v101
	v_mul_f32_e32 v102, v134, v102
	v_mul_f32_e32 v103, v135, v103
	v_fma_f32 v100, v100, v208, v148
	v_fma_f32 v101, v101, v209, v149
	v_fma_f32 v102, v102, v210, v150
	v_fma_f32 v103, v103, v211, v151
	v_cvt_pk_bf16_f32 v234, v100, v101
	v_cvt_pk_bf16_f32 v235, v102, v103
	s_nop 0
	global_store_dwordx2 v243, v[234:235], s[20:21] offset:3072
	v_mul_f32_e32 v104, v104, v232
	v_mul_f32_e32 v105, v105, v232
	v_mul_f32_e32 v106, v106, v232
	v_mul_f32_e32 v107, v107, v232
	v_mul_f32_e32 v104, v136, v104
	v_mul_f32_e32 v105, v137, v105
	v_mul_f32_e32 v106, v138, v106
	v_mul_f32_e32 v107, v139, v107
	v_fma_f32 v104, v104, v212, v152
	v_fma_f32 v105, v105, v213, v153
	v_fma_f32 v106, v106, v214, v154
	v_fma_f32 v107, v107, v215, v155
	v_cvt_pk_bf16_f32 v234, v104, v105
	v_cvt_pk_bf16_f32 v235, v106, v107
	s_nop 0
	global_store_dwordx2 v243, v[234:235], s[22:23] offset:3072
	v_mul_f32_e32 v108, v108, v232
	v_mul_f32_e32 v109, v109, v232
	v_mul_f32_e32 v110, v110, v232
	v_mul_f32_e32 v111, v111, v232
	v_mul_f32_e32 v108, v140, v108
	v_mul_f32_e32 v109, v141, v109
	v_mul_f32_e32 v110, v142, v110
	v_mul_f32_e32 v111, v143, v111
	v_fma_f32 v108, v108, v216, v156
	v_fma_f32 v109, v109, v217, v157
	v_fma_f32 v110, v110, v218, v158
	v_fma_f32 v111, v111, v219, v159
	v_cvt_pk_bf16_f32 v234, v108, v109
	v_cvt_pk_bf16_f32 v235, v110, v111
	s_nop 0
	global_store_dwordx2 v243, v[234:235], s[24:25] offset:3072
	v_mul_f32_e32 v112, v112, v233
	v_mul_f32_e32 v113, v113, v233
	v_mul_f32_e32 v114, v114, v233
	v_mul_f32_e32 v115, v115, v233
	v_mul_f32_e32 v112, v128, v112
	v_mul_f32_e32 v113, v129, v113
	v_mul_f32_e32 v114, v130, v114
	v_mul_f32_e32 v115, v131, v115
	v_fma_f32 v112, v112, v204, v144
	v_fma_f32 v113, v113, v205, v145
	v_fma_f32 v114, v114, v206, v146
	v_fma_f32 v115, v115, v207, v147
	v_cvt_pk_bf16_f32 v234, v112, v113
	v_cvt_pk_bf16_f32 v235, v114, v115
	s_nop 0
	global_store_dwordx2 v244, v[234:235], s[18:19] offset:3072
	v_mul_f32_e32 v116, v116, v233
	v_mul_f32_e32 v117, v117, v233
	v_mul_f32_e32 v118, v118, v233
	v_mul_f32_e32 v119, v119, v233
	v_mul_f32_e32 v116, v132, v116
	v_mul_f32_e32 v117, v133, v117
	v_mul_f32_e32 v118, v134, v118
	v_mul_f32_e32 v119, v135, v119
	v_fma_f32 v116, v116, v208, v148
	v_fma_f32 v117, v117, v209, v149
	v_fma_f32 v118, v118, v210, v150
	v_fma_f32 v119, v119, v211, v151
	v_cvt_pk_bf16_f32 v234, v116, v117
	v_cvt_pk_bf16_f32 v235, v118, v119
	s_nop 0
	global_store_dwordx2 v244, v[234:235], s[20:21] offset:3072
	v_mul_f32_e32 v120, v120, v233
	v_mul_f32_e32 v121, v121, v233
	v_mul_f32_e32 v122, v122, v233
	v_mul_f32_e32 v123, v123, v233
	v_mul_f32_e32 v120, v136, v120
	v_mul_f32_e32 v121, v137, v121
	v_mul_f32_e32 v122, v138, v122
	v_mul_f32_e32 v123, v139, v123
	v_fma_f32 v120, v120, v212, v152
	v_fma_f32 v121, v121, v213, v153
	v_fma_f32 v122, v122, v214, v154
	v_fma_f32 v123, v123, v215, v155
	v_cvt_pk_bf16_f32 v234, v120, v121
	v_cvt_pk_bf16_f32 v235, v122, v123
	s_nop 0
	global_store_dwordx2 v244, v[234:235], s[22:23] offset:3072
	v_mul_f32_e32 v124, v124, v233
	v_mul_f32_e32 v125, v125, v233
	v_mul_f32_e32 v126, v126, v233
	v_mul_f32_e32 v127, v127, v233
	v_mul_f32_e32 v124, v140, v124
	v_mul_f32_e32 v125, v141, v125
	v_mul_f32_e32 v126, v142, v126
	v_mul_f32_e32 v127, v143, v127
	v_fma_f32 v124, v124, v216, v156
	v_fma_f32 v125, v125, v217, v157
	v_fma_f32 v126, v126, v218, v158
	v_fma_f32 v127, v127, v219, v159
	v_cvt_pk_bf16_f32 v234, v124, v125
	v_cvt_pk_bf16_f32 v235, v126, v127
	s_nop 0
	global_store_dwordx2 v244, v[234:235], s[24:25] offset:3072
	s_add_i32 s28, s28, 0x4000
	s_cmp_lt_u32 s28, 0x8000
	s_cbranch_scc1 .Lp0n_loop
	s_mov_b64 s[0:1], exec

; template <int MODE>
; DI void gemm_phase(const Params& p, int layer, int hf, unsigned char* shmc, int tid) {
;     ...
;     f32x4 acc[2][2][4][2];
; #pragma unroll
;     for (int a = 0; a < 2; ++a)
; #pragma unroll
;       for (int b = 0; b < 2; ++b)
; #pragma unroll
;         for (int m = 0; m < 4; ++m)
; #pragma unroll
;           for (int n = 0; n < 2; ++n) acc[a][b][m][n] = (f32x4){0.f, 0.f, 0.f, 0.f};
;     const bf16_t* gA = (MODE == 0) ? A + (size_t)(brow >> 7) * nt * 4096 : A + (size_t)brow * lda; const bf16_t* gB = Bt + (size_t)(bcol >> 7) * nt * 4096;
;     ...
;     if (!pre) { STAGE_ALL(0, 0); STAGE_ALL(1, 1); }
;     STAGE_ALL(2, 2);
.LBB0_692:
	v_mov_b32_e32 v2, v169
	s_lshl_b32 s15, s6, 8
	s_mul_i32 s4, s6, 0x340000
	s_mul_hi_i32 s5, s15, 0x3400
	v_lshlrev_b32_e32 v0, 4, v2
	v_and_b32_e32 v1, 32, v2
	s_add_u32 s4, s35, s4
	v_readlane_b32 s6, v253, 40
	v_add_u32_e32 v4, 32, v0
	v_bfe_u32 v3, v2, 2, 23
	v_bitop3_b32 v0, v0, v1, 48 bitop3:0x6c
	s_addc_u32 s5, s6, s5
	s_lshl_b32 s6, s14, 1
	v_lshrrev_b32_e32 v0, 1, v0
	v_mul_u32_u24_e32 v1, 0x1a00, v3
	s_ashr_i32 s7, s6, 31
	v_or_b32_e32 v0, v1, v0
	s_lshl_b64 s[6:7], s[6:7], 19
	v_readlane_b32 s8, v254, 41
	v_ashrrev_i32_e32 v1, 31, v0
	v_add_u32_e32 v5, 0x4000, v4
	v_readfirstlane_b32 s10, v4
	s_add_u32 s8, s8, s6
	v_readlane_b32 s9, v254, 42
	v_lshl_add_u64 v[0:1], v[0:1], 1, s[4:5]
	v_lshlrev_b32_e32 v2, 3, v2
	s_mov_b32 m0, s10
	v_readfirstlane_b32 s10, v5
	s_addc_u32 s9, s9, s7
	v_ashrrev_i32_e32 v3, 31, v2
	global_load_lds_dwordx4 v[0:1], off
	s_mov_b32 m0, s10
	s_mov_b64 s[10:11], 0x1a0000
	v_add_u32_e32 v5, 0x2000, v4
	v_lshl_add_u64 v[2:3], v[2:3], 1, s[8:9]
	v_lshl_add_u64 v[0:1], v[0:1], 0, s[10:11]
	v_readfirstlane_b32 s10, v5
	global_load_lds_dwordx4 v[2:3], off
	s_mov_b32 m0, s10
	s_mov_b64 s[10:11], 0x80000
	global_load_lds_dwordx4 v[0:1], off
	v_lshl_add_u64 v[0:1], v[2:3], 0, s[10:11]
	v_add_u32_e32 v2, 0x6000, v4
	s_mov_b32 s16, 0
	v_readfirstlane_b32 s10, v2
	s_mov_b32 m0, s10
	v_mov_b32_e32 v2, v169
	global_load_lds_dwordx4 v[0:1], off
	s_movk_i32 s17, 0x60
	v_lshlrev_b32_e32 v0, 4, v2
	v_and_b32_e32 v1, 32, v2
	v_add_u32_e32 v6, 32, v0
	v_bfe_u32 v3, v2, 2, 23
	v_bitop3_b32 v0, v0, v1, 48 bitop3:0x6c
	v_lshrrev_b32_e32 v0, 1, v0
	v_mul_u32_u24_e32 v1, 0x1a00, v3
	v_or_b32_e32 v0, v1, v0
	v_add_u32_e32 v7, 0x8000, v6
	v_ashrrev_i32_e32 v1, 31, v0
	v_lshlrev_b32_e32 v2, 3, v2
	v_lshl_add_u64 v[0:1], v[0:1], 1, s[4:5]
	v_ashrrev_i32_e32 v3, 31, v2
	v_readfirstlane_b32 s10, v7
	v_add_u32_e32 v8, 0xc000, v6
	v_lshl_add_u64 v[4:5], v[0:1], 0, 64
	s_mov_b32 m0, s10
	v_lshl_add_u64 v[2:3], v[2:3], 1, s[8:9]
	s_mov_b64 s[10:11], 0x2000
	global_load_lds_dwordx4 v[4:5], off
	v_lshl_add_u64 v[4:5], v[2:3], 0, s[10:11]
	v_readfirstlane_b32 s10, v8
	s_mov_b32 m0, s10
	s_mov_b64 s[10:11], 0x1a0040
	global_load_lds_dwordx4 v[4:5], off
	v_add_u32_e32 v4, 0xa000, v6
	v_lshl_add_u64 v[0:1], v[0:1], 0, s[10:11]
	v_readfirstlane_b32 s10, v4
	s_mov_b32 m0, s10
	s_mov_b64 s[10:11], 0x82000
	global_load_lds_dwordx4 v[0:1], off
	v_lshl_add_u64 v[0:1], v[2:3], 0, s[10:11]
	v_add_u32_e32 v2, 0xe000, v6
	s_mov_b32 s18, 0x18000
	v_readfirstlane_b32 s10, v2
	s_mov_b32 m0, s10
	v_mov_b32_e32 v2, v169
	global_load_lds_dwordx4 v[0:1], off
	v_readlane_b32 s10, v253, 62
	v_lshlrev_b32_e32 v0, 4, v2
	v_and_b32_e32 v1, 32, v2
	v_add_u32_e32 v6, s10, v0
	v_bfe_u32 v3, v2, 2, 23
	v_bitop3_b32 v0, v0, v1, 48 bitop3:0x6c
	v_lshrrev_b32_e32 v0, 1, v0
	v_mul_u32_u24_e32 v1, 0x1a00, v3
	v_or_b32_e32 v0, v1, v0
	v_ashrrev_i32_e32 v1, 31, v0
	v_lshl_add_u64 v[0:1], v[0:1], 1, s[4:5]
	v_lshlrev_b32_e32 v2, 3, v2
	s_mov_b64 s[10:11], 0x80
	v_ashrrev_i32_e32 v3, 31, v2
	v_lshl_add_u64 v[4:5], v[0:1], 0, s[10:11]
	v_readfirstlane_b32 s10, v6
	v_add_u32_e32 v7, 0x4000, v6
	s_mov_b32 m0, s10
	v_lshl_add_u64 v[2:3], v[2:3], 1, s[8:9]
	s_mov_b64 s[8:9], 0x4000
	global_load_lds_dwordx4 v[4:5], off
	v_lshl_add_u64 v[4:5], v[2:3], 0, s[8:9]
	v_readfirstlane_b32 s8, v7
	s_mov_b32 m0, s8
	s_mov_b64 s[8:9], 0x1a0080
	global_load_lds_dwordx4 v[4:5], off
	v_add_u32_e32 v4, 0x2000, v6
	v_lshl_add_u64 v[0:1], v[0:1], 0, s[8:9]
	v_readfirstlane_b32 s8, v4
	s_mov_b32 m0, s8
	s_mov_b64 s[8:9], 0x84000
	global_load_lds_dwordx4 v[0:1], off
	v_lshl_add_u64 v[0:1], v[2:3], 0, s[8:9]
	v_add_u32_e32 v2, 0x6000, v6
	s_nop 0
	v_readfirstlane_b32 s8, v2
	s_mov_b32 m0, s8
	v_readlane_b32 s8, v253, 60
	global_load_lds_dwordx4 v[0:1], off
	v_mov_b32_e32 v0, 0
	v_readlane_b32 s9, v253, 61
	v_mov_b32_e32 v1, v0
	v_mov_b32_e32 v2, v0
	v_mov_b32_e32 v3, v0
	v_mov_b32_e32 v4, v0
	v_mov_b32_e32 v5, v0
	v_mov_b32_e32 v6, v0
	v_mov_b32_e32 v7, v0
	v_mov_b32_e32 v8, v0
	v_mov_b32_e32 v9, v0
	v_mov_b32_e32 v10, v0
	v_mov_b32_e32 v11, v0
	v_mov_b32_e32 v12, v0
	v_mov_b32_e32 v13, v0
	v_mov_b32_e32 v14, v0
	v_mov_b32_e32 v15, v0
	v_mov_b32_e32 v64, v0
	v_mov_b32_e32 v65, v0
	v_mov_b32_e32 v66, v0
	v_mov_b32_e32 v67, v0
	v_mov_b32_e32 v68, v0
	v_mov_b32_e32 v69, v0
	v_mov_b32_e32 v70, v0
	v_mov_b32_e32 v71, v0
	v_mov_b32_e32 v72, v0
	v_mov_b32_e32 v73, v0
	v_mov_b32_e32 v74, v0
	v_mov_b32_e32 v75, v0
	v_mov_b32_e32 v76, v0
	v_mov_b32_e32 v77, v0
	v_mov_b32_e32 v78, v0
	v_mov_b32_e32 v79, v0
	v_mov_b32_e32 v80, v0
	v_mov_b32_e32 v81, v0
	v_mov_b32_e32 v82, v0
	v_mov_b32_e32 v83, v0
	v_mov_b32_e32 v84, v0
	v_mov_b32_e32 v85, v0
	v_mov_b32_e32 v86, v0
	v_mov_b32_e32 v87, v0
	v_mov_b32_e32 v92, v0
	v_mov_b32_e32 v93, v0
	v_mov_b32_e32 v94, v0
	v_mov_b32_e32 v95, v0
	v_mov_b32_e32 v100, v0
	v_mov_b32_e32 v101, v0
	v_mov_b32_e32 v102, v0
	v_mov_b32_e32 v103, v0
	v_mov_b32_e32 v88, v0
	v_mov_b32_e32 v89, v0
	v_mov_b32_e32 v90, v0
	v_mov_b32_e32 v91, v0
	v_mov_b32_e32 v96, v0
	v_mov_b32_e32 v97, v0
	v_mov_b32_e32 v98, v0
	v_mov_b32_e32 v99, v0
	v_mov_b32_e32 v104, v0
	v_mov_b32_e32 v105, v0
	v_mov_b32_e32 v106, v0
	v_mov_b32_e32 v107, v0
	v_mov_b32_e32 v108, v0
	v_mov_b32_e32 v109, v0
	v_mov_b32_e32 v110, v0
	v_mov_b32_e32 v111, v0
	v_mov_b32_e32 v112, v0
	v_mov_b32_e32 v113, v0
	v_mov_b32_e32 v114, v0
	v_mov_b32_e32 v115, v0
	v_mov_b32_e32 v116, v0
	v_mov_b32_e32 v117, v0
	v_mov_b32_e32 v118, v0
	v_mov_b32_e32 v119, v0
	v_mov_b32_e32 v120, v0
	v_mov_b32_e32 v121, v0
	v_mov_b32_e32 v122, v0
	v_mov_b32_e32 v123, v0
	v_mov_b32_e32 v124, v0
	v_mov_b32_e32 v125, v0
	v_mov_b32_e32 v126, v0
; #define WAIT_V(n) asm volatile("s_waitcnt vmcnt(" #n ")" ::: "memory")
; #define BAR __builtin_amdgcn_s_barrier()
; #define LDA_(dst, ai) _Pragma("unroll") for (int m = 0; m < 4; ++m) dst[m] = *(const bf16x8*)(sb + (ai) * 8192 + la0 + m * 1024)
; #define LDB_(dst) _Pragma("unroll") for (int bj = 0; bj < 2; ++bj) _Pragma("unroll") for (int n = 0; n < 2; ++n) dst[bj][n] = *(const bf16x8*)(sb + 16384 + bj * 8192 + lb0 + n * 1024)
; #define MMA_(ai, bf_, af_) _Pragma("unroll") for (int bj = 0; bj < 2; ++bj) _Pragma("unroll") for (int m = 0; m < 4; ++m) _Pragma("unroll") for (int n = 0; n < 2; ++n) \
;         acc[ai][bj][m][n] = __builtin_amdgcn_mfma_f32_16x16x32_bf16(bf_[bj][n], af_[m], acc[ai][bj][m][n], 0, 0, 0)
; template <int MODE>
; DI void gemm_phase(const Params& p, int layer, int hf, unsigned char* shmc, int tid) {
;     ...
;     for (int kt = 0; kt < nt; ++kt) {
;       const int rem = nt - 1 - kt;
;       if (rem >= 2) WAIT_V(8); else if (rem == 1) WAIT_V(4); else WAIT_V(0);
;       BAR;
;       const unsigned char* sb = shmc + (kt & 3) * 32768;
;     ...
;       {
;         bf16x8 b0[2][2], a0[4], a1[4];
;         LDB_(b0); LDA_(a0, 0);
;         __builtin_amdgcn_sched_barrier(0);
;         LDA_(a1, 1); MMA_(0, b0, a0);
;         __builtin_amdgcn_sched_barrier(0);
;         if (kt + 3 < nt) STAGE_ALL((kt + 3) & 3, kt + 3);
;         __builtin_amdgcn_sched_barrier(0);
;         MMA_(1, b0, a1);
;       }
	v_mov_b32_e32 v127, v0
	v_mov_b32_e32 v16, v0
	v_mov_b32_e32 v17, v0
	v_mov_b32_e32 v18, v0
	v_mov_b32_e32 v19, v0
	v_mov_b32_e32 v20, v0
	v_mov_b32_e32 v21, v0
	v_mov_b32_e32 v22, v0
	v_mov_b32_e32 v23, v0
	v_mov_b32_e32 v24, v0
	v_mov_b32_e32 v25, v0
	v_mov_b32_e32 v26, v0
	v_mov_b32_e32 v27, v0
	v_mov_b32_e32 v28, v0
	v_mov_b32_e32 v29, v0
	v_mov_b32_e32 v30, v0
	v_mov_b32_e32 v31, v0
	v_mov_b32_e32 v32, v0
	v_mov_b32_e32 v33, v0
	v_mov_b32_e32 v34, v0
	v_mov_b32_e32 v35, v0
	v_mov_b32_e32 v36, v0
	v_mov_b32_e32 v37, v0
	v_mov_b32_e32 v38, v0
	v_mov_b32_e32 v39, v0
	v_mov_b32_e32 v40, v0
	v_mov_b32_e32 v41, v0
	v_mov_b32_e32 v42, v0
	v_mov_b32_e32 v43, v0
	v_mov_b32_e32 v44, v0
	v_mov_b32_e32 v45, v0
	v_mov_b32_e32 v46, v0
	v_mov_b32_e32 v47, v0
	v_mov_b32_e32 v48, v0
	v_mov_b32_e32 v49, v0
	v_mov_b32_e32 v50, v0
	v_mov_b32_e32 v51, v0
	v_mov_b32_e32 v52, v0
	v_mov_b32_e32 v53, v0
	v_mov_b32_e32 v54, v0
	v_mov_b32_e32 v55, v0
	v_mov_b32_e32 v56, v0
	v_mov_b32_e32 v57, v0
	v_mov_b32_e32 v58, v0
	v_mov_b32_e32 v59, v0
	v_mov_b32_e32 v60, v0
	v_mov_b32_e32 v61, v0
	v_mov_b32_e32 v62, v0
	v_mov_b32_e32 v63, v0
	v_lshlrev_b32_e32 v183, 4, v169
	v_and_b32_e32 v182, 32, v169
	v_bitop3_b32 v182, v183, v182, 48 bitop3:0x6c
	v_lshrrev_b32_e32 v184, 2, v169
	v_lshrrev_b32_e32 v182, 1, v182
	v_mul_u32_u24_e32 v184, 0x1a00, v184
	v_readfirstlane_b32 s29, v183
	v_add_u32_e32 v182, v182, v184
	v_lshlrev_b32_e32 v182, 1, v182
	v_add_u32_e32 v184, 32, v173
	v_add_u32_e32 v185, 0x10020, v173
	v_add3_u32 v186, v174, v172, 32
	s_add_u32 s98, s4, 0xc0
	s_addc_u32 s99, s5, 0
	s_add_u32 s100, s8, s6
	s_addc_u32 s101, s9, s7
	v_add_u32_e32 v187, 0x10000, v186
	s_add_i32 s29, s29, 32
	s_mov_b32 s28, 0
	s_waitcnt vmcnt(8)
	s_barrier
	ds_read_b128 v[140:143], v186 offset:16384
	ds_read_b128 v[144:147], v186 offset:17408
	ds_read_b128 v[132:135], v186 offset:24576
	ds_read_b128 v[128:131], v186 offset:25600
	ds_read_b128 v[136:139], v184
	ds_read_b128 v[148:151], v184 offset:1024
	ds_read_b128 v[152:155], v184 offset:2048
	ds_read_b128 v[178:181], v184 offset:3072
.Lg1_loop:
	s_waitcnt vmcnt(4)
	s_barrier
	ds_read_b128 v[156:159], v184 offset:8192
	ds_read_b128 v[236:239], v184 offset:9216
	ds_read_b128 v[240:243], v184 offset:10240
	ds_read_b128 v[244:247], v184 offset:11264
	s_waitcnt lgkmcnt(4)
	v_mfma_f32_16x16x32_bf16 v[124:127], v[140:143], v[136:139], v[124:127]
	v_mfma_f32_16x16x32_bf16 v[120:123], v[144:147], v[136:139], v[120:123]
	ds_read_b128 v[204:207], v186 offset:49152
	v_mfma_f32_16x16x32_bf16 v[116:119], v[140:143], v[148:151], v[116:119]
	v_mfma_f32_16x16x32_bf16 v[112:115], v[144:147], v[148:151], v[112:115]
	ds_read_b128 v[208:211], v186 offset:50176
	v_mfma_f32_16x16x32_bf16 v[108:111], v[140:143], v[152:155], v[108:111]
	v_mfma_f32_16x16x32_bf16 v[104:107], v[144:147], v[152:155], v[104:107]
	ds_read_b128 v[212:215], v186 offset:57344
	v_mfma_f32_16x16x32_bf16 v[100:103], v[132:135], v[136:139], v[100:103]
	v_mfma_f32_16x16x32_bf16 v[92:95], v[128:131], v[136:139], v[92:95]
	ds_read_b128 v[216:219], v186 offset:58368
	v_mfma_f32_16x16x32_bf16 v[84:87], v[132:135], v[148:151], v[84:87]
	v_mfma_f32_16x16x32_bf16 v[80:83], v[128:131], v[148:151], v[80:83]
	ds_read_b128 v[220:223], v184 offset:32768
	v_mfma_f32_16x16x32_bf16 v[76:79], v[132:135], v[152:155], v[76:79]
	v_mfma_f32_16x16x32_bf16 v[72:75], v[128:131], v[152:155], v[72:75]
	ds_read_b128 v[224:227], v184 offset:33792
	v_mfma_f32_16x16x32_bf16 v[96:99], v[140:143], v[178:181], v[96:99]
	v_mfma_f32_16x16x32_bf16 v[88:91], v[144:147], v[178:181], v[88:91]
	ds_read_b128 v[228:231], v184 offset:34816
	v_mfma_f32_16x16x32_bf16 v[68:71], v[132:135], v[178:181], v[68:71]
	v_mfma_f32_16x16x32_bf16 v[64:67], v[128:131], v[178:181], v[64:67]
	ds_read_b128 v[232:235], v184 offset:35840
	s_add_u32 m0, s29, 0x18000
	s_add_u32 s0, s98, 0x1a0000
	s_addc_u32 s1, s99, 0
	global_load_lds_dwordx4 v182, s[98:99]
	s_add_u32 m0, s29, 0x1c000
	s_add_u32 s10, s100, 0x80000
	s_addc_u32 s11, s101, 0
	global_load_lds_dwordx4 v183, s[100:101]
	s_add_u32 m0, s29, 0x1a000
	s_add_u32 s98, s98, 64
	s_addc_u32 s99, s99, 0
	global_load_lds_dwordx4 v182, s[0:1]
	s_add_u32 m0, s29, 0x1e000
	s_add_u32 s100, s100, 0x2000
	s_addc_u32 s101, s101, 0
	global_load_lds_dwordx4 v183, s[10:11]
	s_waitcnt lgkmcnt(8)
	v_mfma_f32_16x16x32_bf16 v[12:15], v[140:143], v[156:159], v[12:15]
	v_mfma_f32_16x16x32_bf16 v[8:11], v[144:147], v[156:159], v[8:11]
	v_mfma_f32_16x16x32_bf16 v[4:7], v[140:143], v[236:239], v[4:7]
	v_mfma_f32_16x16x32_bf16 v[0:3], v[144:147], v[236:239], v[0:3]
	v_mfma_f32_16x16x32_bf16 v[16:19], v[140:143], v[240:243], v[16:19]
	v_mfma_f32_16x16x32_bf16 v[20:23], v[144:147], v[240:243], v[20:23]
	v_mfma_f32_16x16x32_bf16 v[24:27], v[140:143], v[244:247], v[24:27]
	v_mfma_f32_16x16x32_bf16 v[28:31], v[144:147], v[244:247], v[28:31]
	v_mfma_f32_16x16x32_bf16 v[32:35], v[132:135], v[156:159], v[32:35]
	v_mfma_f32_16x16x32_bf16 v[36:39], v[128:131], v[156:159], v[36:39]
	v_mfma_f32_16x16x32_bf16 v[40:43], v[132:135], v[236:239], v[40:43]
	v_mfma_f32_16x16x32_bf16 v[44:47], v[128:131], v[236:239], v[44:47]
	v_mfma_f32_16x16x32_bf16 v[48:51], v[132:135], v[240:243], v[48:51]
	v_mfma_f32_16x16x32_bf16 v[52:55], v[128:131], v[240:243], v[52:55]
	v_mfma_f32_16x16x32_bf16 v[56:59], v[132:135], v[244:247], v[56:59]
	v_mfma_f32_16x16x32_bf16 v[60:63], v[128:131], v[244:247], v[60:63]
	s_waitcnt vmcnt(4)
	s_barrier
; #define WAIT_V(n) asm volatile("s_waitcnt vmcnt(" #n ")" ::: "memory")
; #define BAR __builtin_amdgcn_s_barrier()
; #define LDA_(dst, ai) _Pragma("unroll") for (int m = 0; m < 4; ++m) dst[m] = *(const bf16x8*)(sb + (ai) * 8192 + la0 + m * 1024)
; #define LDB_(dst) _Pragma("unroll") for (int bj = 0; bj < 2; ++bj) _Pragma("unroll") for (int n = 0; n < 2; ++n) dst[bj][n] = *(const bf16x8*)(sb + 16384 + bj * 8192 + lb0 + n * 1024)
; #define MMA_(ai, bf_, af_) _Pragma("unroll") for (int bj = 0; bj < 2; ++bj) _Pragma("unroll") for (int m = 0; m < 4; ++m) _Pragma("unroll") for (int n = 0; n < 2; ++n) \
;         acc[ai][bj][m][n] = __builtin_amdgcn_mfma_f32_16x16x32_bf16(bf_[bj][n], af_[m], acc[ai][bj][m][n], 0, 0, 0)
; template <int MODE>
; DI void gemm_phase(const Params& p, int layer, int hf, unsigned char* shmc, int tid) {
;     ...
;     for (int kt = 0; kt < nt; ++kt) {
;       const int rem = nt - 1 - kt;
;       if (rem >= 2) WAIT_V(8); else if (rem == 1) WAIT_V(4); else WAIT_V(0);
;       BAR;
;       const unsigned char* sb = shmc + (kt & 3) * 32768;
;     ...
;       {
;         bf16x8 b0[2][2], a0[4], a1[4];
;         LDB_(b0); LDA_(a0, 0);
;         __builtin_amdgcn_sched_barrier(0);
;         LDA_(a1, 1); MMA_(0, b0, a0);
;         __builtin_amdgcn_sched_barrier(0);
;         if (kt + 3 < nt) STAGE_ALL((kt + 3) & 3, kt + 3);
;         __builtin_amdgcn_sched_barrier(0);
;         MMA_(1, b0, a1);
;       }
	ds_read_b128 v[156:159], v184 offset:40960
	ds_read_b128 v[236:239], v184 offset:41984
	ds_read_b128 v[240:243], v184 offset:43008
	ds_read_b128 v[244:247], v184 offset:44032
	s_waitcnt lgkmcnt(4)
	v_mfma_f32_16x16x32_bf16 v[124:127], v[204:207], v[220:223], v[124:127]
	v_mfma_f32_16x16x32_bf16 v[120:123], v[208:211], v[220:223], v[120:123]
	ds_read_b128 v[140:143], v187 offset:16384
	v_mfma_f32_16x16x32_bf16 v[116:119], v[204:207], v[224:227], v[116:119]
	v_mfma_f32_16x16x32_bf16 v[112:115], v[208:211], v[224:227], v[112:115]
	ds_read_b128 v[144:147], v187 offset:17408
	v_mfma_f32_16x16x32_bf16 v[108:111], v[204:207], v[228:231], v[108:111]
	v_mfma_f32_16x16x32_bf16 v[104:107], v[208:211], v[228:231], v[104:107]
	ds_read_b128 v[132:135], v187 offset:24576
	v_mfma_f32_16x16x32_bf16 v[100:103], v[212:215], v[220:223], v[100:103]
	v_mfma_f32_16x16x32_bf16 v[92:95], v[216:219], v[220:223], v[92:95]
	ds_read_b128 v[128:131], v187 offset:25600
	v_mfma_f32_16x16x32_bf16 v[84:87], v[212:215], v[224:227], v[84:87]
	v_mfma_f32_16x16x32_bf16 v[80:83], v[216:219], v[224:227], v[80:83]
	ds_read_b128 v[136:139], v185
	v_mfma_f32_16x16x32_bf16 v[76:79], v[212:215], v[228:231], v[76:79]
	v_mfma_f32_16x16x32_bf16 v[72:75], v[216:219], v[228:231], v[72:75]
	ds_read_b128 v[148:151], v185 offset:1024
	v_mfma_f32_16x16x32_bf16 v[96:99], v[204:207], v[232:235], v[96:99]
	v_mfma_f32_16x16x32_bf16 v[88:91], v[208:211], v[232:235], v[88:91]
	ds_read_b128 v[152:155], v185 offset:2048
	v_mfma_f32_16x16x32_bf16 v[68:71], v[212:215], v[232:235], v[68:71]
	v_mfma_f32_16x16x32_bf16 v[64:67], v[216:219], v[232:235], v[64:67]
	ds_read_b128 v[178:181], v185 offset:3072
	s_cmp_ge_u32 s28, 60
	s_cbranch_scc1 .Lg1_nost_1
	s_mov_b32 m0, s29
	s_add_u32 s0, s98, 0x1a0000
	s_addc_u32 s1, s99, 0
	global_load_lds_dwordx4 v182, s[98:99]
	s_add_u32 m0, s29, 0x4000
	s_add_u32 s10, s100, 0x80000
	s_addc_u32 s11, s101, 0
	global_load_lds_dwordx4 v183, s[100:101]
	s_add_u32 m0, s29, 0x2000
	s_add_u32 s98, s98, 64
	s_addc_u32 s99, s99, 0
	global_load_lds_dwordx4 v182, s[0:1]
	s_add_u32 m0, s29, 0x6000
	s_add_u32 s100, s100, 0x2000
	s_addc_u32 s101, s101, 0
	global_load_lds_dwordx4 v183, s[10:11]
.Lg1_nost_1:
	s_waitcnt lgkmcnt(8)
	v_mfma_f32_16x16x32_bf16 v[12:15], v[204:207], v[156:159], v[12:15]
	v_mfma_f32_16x16x32_bf16 v[8:11], v[208:211], v[156:159], v[8:11]
	v_mfma_f32_16x16x32_bf16 v[4:7], v[204:207], v[236:239], v[4:7]
	v_mfma_f32_16x16x32_bf16 v[0:3], v[208:211], v[236:239], v[0:3]
	v_mfma_f32_16x16x32_bf16 v[16:19], v[204:207], v[240:243], v[16:19]
	v_mfma_f32_16x16x32_bf16 v[20:23], v[208:211], v[240:243], v[20:23]
	v_mfma_f32_16x16x32_bf16 v[24:27], v[204:207], v[244:247], v[24:27]
	v_mfma_f32_16x16x32_bf16 v[28:31], v[208:211], v[244:247], v[28:31]
	v_mfma_f32_16x16x32_bf16 v[32:35], v[212:215], v[156:159], v[32:35]
	v_mfma_f32_16x16x32_bf16 v[36:39], v[216:219], v[156:159], v[36:39]
	v_mfma_f32_16x16x32_bf16 v[40:43], v[212:215], v[236:239], v[40:43]
	v_mfma_f32_16x16x32_bf16 v[44:47], v[216:219], v[236:239], v[44:47]
	v_mfma_f32_16x16x32_bf16 v[48:51], v[212:215], v[240:243], v[48:51]
	v_mfma_f32_16x16x32_bf16 v[52:55], v[216:219], v[240:243], v[52:55]
	v_mfma_f32_16x16x32_bf16 v[56:59], v[212:215], v[244:247], v[56:59]
	v_mfma_f32_16x16x32_bf16 v[60:63], v[216:219], v[244:247], v[60:63]
	s_cmp_lt_u32 s28, 60
	s_cbranch_scc1 .Lg1_w4_2
	s_waitcnt vmcnt(0)
.Lg1_w4_2:
	s_waitcnt vmcnt(4)
	s_barrier
	ds_read_b128 v[156:159], v185 offset:8192
	ds_read_b128 v[236:239], v185 offset:9216
	ds_read_b128 v[240:243], v185 offset:10240
	ds_read_b128 v[244:247], v185 offset:11264
	s_waitcnt lgkmcnt(4)
	v_mfma_f32_16x16x32_bf16 v[124:127], v[140:143], v[136:139], v[124:127]
	v_mfma_f32_16x16x32_bf16 v[120:123], v[144:147], v[136:139], v[120:123]
	ds_read_b128 v[204:207], v187 offset:49152
	v_mfma_f32_16x16x32_bf16 v[116:119], v[140:143], v[148:151], v[116:119]
	v_mfma_f32_16x16x32_bf16 v[112:115], v[144:147], v[148:151], v[112:115]
	ds_read_b128 v[208:211], v187 offset:50176
	v_mfma_f32_16x16x32_bf16 v[108:111], v[140:143], v[152:155], v[108:111]
	v_mfma_f32_16x16x32_bf16 v[104:107], v[144:147], v[152:155], v[104:107]
	ds_read_b128 v[212:215], v187 offset:57344
	v_mfma_f32_16x16x32_bf16 v[100:103], v[132:135], v[136:139], v[100:103]
	v_mfma_f32_16x16x32_bf16 v[92:95], v[128:131], v[136:139], v[92:95]
	ds_read_b128 v[216:219], v187 offset:58368
	v_mfma_f32_16x16x32_bf16 v[84:87], v[132:135], v[148:151], v[84:87]
	v_mfma_f32_16x16x32_bf16 v[80:83], v[128:131], v[148:151], v[80:83]
	ds_read_b128 v[220:223], v185 offset:32768
	v_mfma_f32_16x16x32_bf16 v[76:79], v[132:135], v[152:155], v[76:79]
	v_mfma_f32_16x16x32_bf16 v[72:75], v[128:131], v[152:155], v[72:75]
	ds_read_b128 v[224:227], v185 offset:33792
	v_mfma_f32_16x16x32_bf16 v[96:99], v[140:143], v[178:181], v[96:99]
	v_mfma_f32_16x16x32_bf16 v[88:91], v[144:147], v[178:181], v[88:91]
	ds_read_b128 v[228:231], v185 offset:34816
	v_mfma_f32_16x16x32_bf16 v[68:71], v[132:135], v[178:181], v[68:71]
	v_mfma_f32_16x16x32_bf16 v[64:67], v[128:131], v[178:181], v[64:67]
	ds_read_b128 v[232:235], v185 offset:35840
	s_cmp_ge_u32 s28, 60
	s_cbranch_scc1 .Lg1_nost_2
	s_add_u32 m0, s29, 0x8000
	s_add_u32 s0, s98, 0x1a0000
	s_addc_u32 s1, s99, 0
	global_load_lds_dwordx4 v182, s[98:99]
	s_add_u32 m0, s29, 0xc000
	s_add_u32 s10, s100, 0x80000
	s_addc_u32 s11, s101, 0
	global_load_lds_dwordx4 v183, s[100:101]
	s_add_u32 m0, s29, 0xa000
	s_add_u32 s98, s98, 64
	s_addc_u32 s99, s99, 0
	global_load_lds_dwordx4 v182, s[0:1]
	s_add_u32 m0, s29, 0xe000
	s_add_u32 s100, s100, 0x2000
	s_addc_u32 s101, s101, 0
	global_load_lds_dwordx4 v183, s[10:11]
; #define WAIT_V(n) asm volatile("s_waitcnt vmcnt(" #n ")" ::: "memory")
; #define BAR __builtin_amdgcn_s_barrier()
; #define LDA_(dst, ai) _Pragma("unroll") for (int m = 0; m < 4; ++m) dst[m] = *(const bf16x8*)(sb + (ai) * 8192 + la0 + m * 1024)
; #define LDB_(dst) _Pragma("unroll") for (int bj = 0; bj < 2; ++bj) _Pragma("unroll") for (int n = 0; n < 2; ++n) dst[bj][n] = *(const bf16x8*)(sb + 16384 + bj * 8192 + lb0 + n * 1024)
; #define MMA_(ai, bf_, af_) _Pragma("unroll") for (int bj = 0; bj < 2; ++bj) _Pragma("unroll") for (int m = 0; m < 4; ++m) _Pragma("unroll") for (int n = 0; n < 2; ++n) \
;         acc[ai][bj][m][n] = __builtin_amdgcn_mfma_f32_16x16x32_bf16(bf_[bj][n], af_[m], acc[ai][bj][m][n], 0, 0, 0)
; template <int MODE>
; DI void gemm_phase(const Params& p, int layer, int hf, unsigned char* shmc, int tid) {
;     ...
;     for (int kt = 0; kt < nt; ++kt) {
;       const int rem = nt - 1 - kt;
;       if (rem >= 2) WAIT_V(8); else if (rem == 1) WAIT_V(4); else WAIT_V(0);
;       BAR;
;       const unsigned char* sb = shmc + (kt & 3) * 32768;
;     ...
;       {
;         bf16x8 b0[2][2], a0[4], a1[4];
;         LDB_(b0); LDA_(a0, 0);
;         __builtin_amdgcn_sched_barrier(0);
;         LDA_(a1, 1); MMA_(0, b0, a0);
;         __builtin_amdgcn_sched_barrier(0);
;         if (kt + 3 < nt) STAGE_ALL((kt + 3) & 3, kt + 3);
;         __builtin_amdgcn_sched_barrier(0);
;         MMA_(1, b0, a1);
;       }
;     ...
;     }
.Lg1_nost_2:
	s_waitcnt lgkmcnt(8)
	v_mfma_f32_16x16x32_bf16 v[12:15], v[140:143], v[156:159], v[12:15]
	v_mfma_f32_16x16x32_bf16 v[8:11], v[144:147], v[156:159], v[8:11]
	v_mfma_f32_16x16x32_bf16 v[4:7], v[140:143], v[236:239], v[4:7]
	v_mfma_f32_16x16x32_bf16 v[0:3], v[144:147], v[236:239], v[0:3]
	v_mfma_f32_16x16x32_bf16 v[16:19], v[140:143], v[240:243], v[16:19]
	v_mfma_f32_16x16x32_bf16 v[20:23], v[144:147], v[240:243], v[20:23]
	v_mfma_f32_16x16x32_bf16 v[24:27], v[140:143], v[244:247], v[24:27]
	v_mfma_f32_16x16x32_bf16 v[28:31], v[144:147], v[244:247], v[28:31]
	v_mfma_f32_16x16x32_bf16 v[32:35], v[132:135], v[156:159], v[32:35]
	v_mfma_f32_16x16x32_bf16 v[36:39], v[128:131], v[156:159], v[36:39]
	v_mfma_f32_16x16x32_bf16 v[40:43], v[132:135], v[236:239], v[40:43]
	v_mfma_f32_16x16x32_bf16 v[44:47], v[128:131], v[236:239], v[44:47]
	v_mfma_f32_16x16x32_bf16 v[48:51], v[132:135], v[240:243], v[48:51]
	v_mfma_f32_16x16x32_bf16 v[52:55], v[128:131], v[240:243], v[52:55]
	v_mfma_f32_16x16x32_bf16 v[56:59], v[132:135], v[244:247], v[56:59]
	v_mfma_f32_16x16x32_bf16 v[60:63], v[128:131], v[244:247], v[60:63]
	s_cmp_lt_u32 s28, 60
	s_cbranch_scc1 .Lg1_w4_3
	s_waitcnt vmcnt(0)
.Lg1_w4_3:
	s_waitcnt vmcnt(4)
	s_barrier
	ds_read_b128 v[156:159], v185 offset:40960
	ds_read_b128 v[236:239], v185 offset:41984
	ds_read_b128 v[240:243], v185 offset:43008
	ds_read_b128 v[244:247], v185 offset:44032
	s_waitcnt lgkmcnt(4)
	v_mfma_f32_16x16x32_bf16 v[124:127], v[204:207], v[220:223], v[124:127]
	v_mfma_f32_16x16x32_bf16 v[120:123], v[208:211], v[220:223], v[120:123]
	ds_read_b128 v[140:143], v186 offset:16384
	v_mfma_f32_16x16x32_bf16 v[116:119], v[204:207], v[224:227], v[116:119]
	v_mfma_f32_16x16x32_bf16 v[112:115], v[208:211], v[224:227], v[112:115]
	ds_read_b128 v[144:147], v186 offset:17408
	v_mfma_f32_16x16x32_bf16 v[108:111], v[204:207], v[228:231], v[108:111]
	v_mfma_f32_16x16x32_bf16 v[104:107], v[208:211], v[228:231], v[104:107]
	ds_read_b128 v[132:135], v186 offset:24576
	v_mfma_f32_16x16x32_bf16 v[100:103], v[212:215], v[220:223], v[100:103]
	v_mfma_f32_16x16x32_bf16 v[92:95], v[216:219], v[220:223], v[92:95]
	ds_read_b128 v[128:131], v186 offset:25600
	v_mfma_f32_16x16x32_bf16 v[84:87], v[212:215], v[224:227], v[84:87]
	v_mfma_f32_16x16x32_bf16 v[80:83], v[216:219], v[224:227], v[80:83]
	ds_read_b128 v[136:139], v184
	v_mfma_f32_16x16x32_bf16 v[76:79], v[212:215], v[228:231], v[76:79]
	v_mfma_f32_16x16x32_bf16 v[72:75], v[216:219], v[228:231], v[72:75]
	ds_read_b128 v[148:151], v184 offset:1024
	v_mfma_f32_16x16x32_bf16 v[96:99], v[204:207], v[232:235], v[96:99]
	v_mfma_f32_16x16x32_bf16 v[88:91], v[208:211], v[232:235], v[88:91]
	ds_read_b128 v[152:155], v184 offset:2048
	v_mfma_f32_16x16x32_bf16 v[68:71], v[212:215], v[232:235], v[68:71]
	v_mfma_f32_16x16x32_bf16 v[64:67], v[216:219], v[232:235], v[64:67]
	ds_read_b128 v[178:181], v184 offset:3072
	s_cmp_ge_u32 s28, 60
	s_cbranch_scc1 .Lg1_nost_3
	s_add_u32 m0, s29, 0x10000
	s_add_u32 s0, s98, 0x1a0000
	s_addc_u32 s1, s99, 0
	global_load_lds_dwordx4 v182, s[98:99]
	s_add_u32 m0, s29, 0x14000
	s_add_u32 s10, s100, 0x80000
	s_addc_u32 s11, s101, 0
	global_load_lds_dwordx4 v183, s[100:101]
	s_add_u32 m0, s29, 0x12000
	s_add_u32 s98, s98, 64
	s_addc_u32 s99, s99, 0
	global_load_lds_dwordx4 v182, s[0:1]
	s_add_u32 m0, s29, 0x16000
	s_add_u32 s100, s100, 0x2000
	s_addc_u32 s101, s101, 0
	global_load_lds_dwordx4 v183, s[10:11]
.Lg1_nost_3:
	s_waitcnt lgkmcnt(8)
	v_mfma_f32_16x16x32_bf16 v[12:15], v[204:207], v[156:159], v[12:15]
	v_mfma_f32_16x16x32_bf16 v[8:11], v[208:211], v[156:159], v[8:11]
	v_mfma_f32_16x16x32_bf16 v[4:7], v[204:207], v[236:239], v[4:7]
	v_mfma_f32_16x16x32_bf16 v[0:3], v[208:211], v[236:239], v[0:3]
	v_mfma_f32_16x16x32_bf16 v[16:19], v[204:207], v[240:243], v[16:19]
	v_mfma_f32_16x16x32_bf16 v[20:23], v[208:211], v[240:243], v[20:23]
	v_mfma_f32_16x16x32_bf16 v[24:27], v[204:207], v[244:247], v[24:27]
	v_mfma_f32_16x16x32_bf16 v[28:31], v[208:211], v[244:247], v[28:31]
	v_mfma_f32_16x16x32_bf16 v[32:35], v[212:215], v[156:159], v[32:35]
	v_mfma_f32_16x16x32_bf16 v[36:39], v[216:219], v[156:159], v[36:39]
	v_mfma_f32_16x16x32_bf16 v[40:43], v[212:215], v[236:239], v[40:43]
	v_mfma_f32_16x16x32_bf16 v[44:47], v[216:219], v[236:239], v[44:47]
	v_mfma_f32_16x16x32_bf16 v[48:51], v[212:215], v[240:243], v[48:51]
	v_mfma_f32_16x16x32_bf16 v[52:55], v[216:219], v[240:243], v[52:55]
	v_mfma_f32_16x16x32_bf16 v[56:59], v[212:215], v[244:247], v[56:59]
	v_mfma_f32_16x16x32_bf16 v[60:63], v[216:219], v[244:247], v[60:63]
	s_add_i32 s28, s28, 4
	s_cmp_lt_u32 s28, 64
	s_cbranch_scc1 .Lg1_loop
	s_waitcnt lgkmcnt(0)
	v_readlane_b32 s19, v254, 32
